# attention rewritten: QK^T+softmax computed once per map, PV for both 64-col V halves in one unit (d128), hand-generated step code
# speedup vs baseline: 1.1373x; 1.1373x over previous
; #define GASP __attribute__((address_space(1)))
; #define WAIT_BAR(N) asm volatile("s_waitcnt vmcnt(" #N ") lgkmcnt(0)\n\ts_barrier":::"memory")
;   #define CMASK(P0,P1,t) do{}while(0)
; template<int THRL> __device__ __forceinline__ void attn_unit(int b,int qc,int vc,int qb,const bf16*Q,const bf16*__restrict__ K,const bf16*__restrict__ V,bf16*O,char*shm,const int tid){
;   const int lane=tid&63,r32=lane&31,hi=lane>>5; const int wid=__builtin_amdgcn_readfirstlane(tid>>6);
;   const long rowbase=(long)b*SEQ; const int q0=qb*QB;
;   const bf16*Qw=Q+(rowbase+q0+wid*QBLK)*DM+qc;
;   const bf16*Kh=K+rowbase*DM+qc,*Vh=V+rowbase*DM+vc;
;   const unsigned lds0=(unsigned)(uintptr_t)shm;
;   float*wsf=(float*)(shm+LDS_WS)+wid*64;
;   const bf16*ksrc=Kh+(long)lane*DM+wid*8;
;   const bf16*vsrc=Vh+(long)(16*(wid&3)+(lane>>2))*DM+(wid>>2)*32+(lane&3)*8;
;   const unsigned kdst=lds0+LDS_K+wid*1024, vdst=lds0+LDS_V+wid*1024;
;     ...
;   const int vb0=(int)(lds0+LDS_V)+((lane>>4)&1)*32+(lane&3)*8+(4*hi+((lane&15)>>2))*64;
;   const char*Kbase=shm+LDS_K; bf16x8 kf[8];
;   const lds_cptr shm3=(lds_cptr)shm; const lds_cptr kp0=shm3+LDS_K+hi*1024+r32*16; const lds_cptr vp0=shm3+LDS_V+((lane>>4)&1)*32+(lane&3)*8+(4*hi+((lane&15)>>2))*64;
;   const int NT=(q0+QB)/KVBLK;
;   DMA_K(0,0);DMA_V(0,0);DMA_K(1,SLOTB);
;   bf16x8 qr[4];
;   #pragma unroll
;   for(int d0=0;d0<4;++d0)qr[d0]=*(const GASP bf16x8*)(&Qw[(long)r32*DM+d0*16+hi*8]);
;   float zf_=0.f;asm volatile("":"+v"(zf_));float mhat=zf_,l_reg=zf_;f32x16 o[2],negm;
;   #pragma unroll
;   for(int r=0;r<16;++r){o[0][r]=zf_;o[1][r]=zf_;negm[r]=zf_;}
;   asm volatile("":"+v"(negm));
;   const int qrel=wid*QBLK+r32;
;     ...
;   bool resc=false;
;     ...
;   f32x16 pA0,pA1,pB0,pB1;
;   int sl_prev=0,sl_cur=0,sl_next=SLOTB;
;     ...
;   DMA_K(2,2*SLOTB);
;   WAIT_BAR(3);
;   qkt(pA0,pA1,Kbase,qr,negm,r32,hi);asm volatile("s_nop 15\n\ts_nop 7":"+v"(pA0),"+v"(pA1));CMASK(pA0,pA1,0);
; __global__ void __launch_bounds__(NWAVES * 64, 2) fwd_kernel(Args args) {
;     ...
;                 for (int cm = 0; cm < 4; ++cm) { const int mp = cm >> 1, vh = cm & 1;
;                     for (int qi = 0; qi < 4; ++qi) {
;                         const int qb = (qi == 0) ? 15 - s4 : (qi == 1) ? 8 + s4 : (qi == 2) ? 7 - s4 : s4;
;                         int t2 = tidp; asm volatile("" : "+v"(t2));
;                         unsigned char* w2 = ws; asm volatile("" : "+s"(w2));
.LBB0_399:
	s_ashr_i32 s0, s56, 5
	s_lshl_b32 s1, s56, 5
	s_and_b32 s61, s1, 0x380
	s_ashr_i32 s1, s0, 31
	s_and_b32 s57, s56, 3
	s_lshl_b64 s[4:5], s[0:1], 22
	s_and_b32 s62, s49, 0x380
	s_or_b32 s58, s57, 8
	s_xor_b32 s59, s57, 15
	s_xor_b32 s60, s57, 7
	s_lshl_b64 s[14:15], s[0:1], 12
	s_mov_b32 s75, s0
	s_mov_b32 s72, 0
.Lat_mp_loop:
	s_mov_b32 s73, 0
.Lat_qi_loop:
.Lat_unit:
	s_cmp_eq_u32 s73, 0
	s_cselect_b32 s36, s59, s57
	s_cmp_eq_u32 s73, 1
	s_cselect_b32 s36, s58, s36
	s_cmp_eq_u32 s73, 2
	s_cselect_b32 s36, s60, s36
	s_lshl_b32 s54, s46, 5
	s_mov_b32 s6, s75
	s_mov_b32 s7, 0
	s_lshl_b64 s[6:7], s[6:7], 23
	s_add_u32 s6, s6, s8
	s_addc_u32 s7, s7, s9
	s_lshl_b32 s32, s61, 1
	s_lshl_b32 s21, s72, 7
	s_add_i32 s21, s21, s32
	s_add_u32 s0, s6, 0x29a00000
	s_addc_u32 s1, s7, 0
	s_add_u32 s0, s0, s21
	s_addc_u32 s1, s1, 0
	s_add_u32 s4, s6, 0x2da00000
	s_addc_u32 s5, s7, 0
	s_add_u32 s4, s4, s32
	s_addc_u32 s5, s5, 0
	s_lshl_b32 s37, s36, 19
	s_add_u32 s30, s6, 0x25a00000
	s_addc_u32 s31, s7, 0
	s_add_u32 s30, s30, s37
	s_addc_u32 s31, s31, 0
	s_add_u32 s30, s30, s21
	s_addc_u32 s31, s31, 0
	s_add_u32 s6, s6, 0xda00000
	s_addc_u32 s7, s7, 0
	s_add_u32 s6, s6, s37
	s_addc_u32 s7, s7, 0
	s_add_u32 s6, s6, s32
	s_addc_u32 s7, s7, 0
	s_lshl_b32 s21, s72, 26
	s_add_u32 s6, s6, s21
	s_addc_u32 s7, s7, 0
	s_lshr_b32 s21, s46, 1
	v_lshlrev_b32_e32 v222, 11, v239
	v_add_u32_e32 v222, s21, v222
	s_lshr_b32 s21, s46, 5
	s_and_b32 s32, s21, 3
	s_lshl_b32 s32, s32, 15
	s_lshr_b32 s37, s21, 2
	s_lshl_b32 s37, s37, 6
	s_or_b32 s32, s32, s37
	v_lshrrev_b32_e32 v243, 2, v239
	v_lshlrev_b32_e32 v243, 11, v243
	v_and_b32_e32 v244, 3, v239
	v_lshl_or_b32 v223, v244, 4, v243
	v_or_b32_e32 v223, s32, v223
	v_add_u32_e32 v224, 0x80, v223
	v_lshrrev_b32_e32 v243, 5, v239
	v_and_b32_e32 v244, 31, v239
	v_add_u32_e32 v253, s46, v244
	v_lshlrev_b32_e32 v252, 11, v253
	v_lshl_or_b32 v252, v243, 4, v252
	v_lshlrev_b32_e32 v225, 2, v243
	v_sub_u32_e32 v225, v253, v225
	v_lshlrev_b32_e32 v219, 4, v244
	v_lshl_or_b32 v219, v243, 10, v219
	s_lshl_b32 s21, s46, 3
	s_add_i32 s21, s21, 0x12000
	v_lshl_add_u32 v226, v244, 2, s21
	v_lshl_add_u32 v227, v243, 4, s21
	s_lshl_b32 s21, s46, 7
	s_add_i32 s21, s21, 0x12800
	v_lshl_add_u32 v228, v244, 1, s21
	v_lshl_add_u32 v228, v243, 9, v228
	v_lshrrev_b32_e32 v253, 3, v239
	v_and_b32_e32 v244, 7, v239
	v_lshlrev_b32_e32 v244, 4, v244
	v_lshl_add_u32 v229, v253, 7, s21
	v_add_u32_e32 v229, v229, v244
	v_add_u32_e32 v253, s46, v253
	v_lshl_or_b32 v251, v253, 11, v244
	v_bfe_u32 v244, v239, 4, 1
	v_lshlrev_b32_e32 v244, 5, v244
	v_and_b32_e32 v253, 3, v239
	v_lshl_or_b32 v244, v253, 3, v244
	v_bfe_u32 v253, v239, 2, 2
	v_lshl_add_u32 v253, v243, 2, v253
	v_lshl_or_b32 v204, v253, 6, v244
	v_mov_b32_e32 v241, 0xff800000
	v_mov_b32_e32 v210, 0
	v_mov_b32_e32 v211, 0
	s_mov_b32 m0, s54
	s_nop 0
	global_load_lds_dwordx4 v222, s[0:1]
	s_add_u32 s0, s0, 0x20000
	s_addc_u32 s1, s1, 0
	s_add_i32 m0, s54, 0x6000
	s_nop 0
	global_load_lds_dwordx4 v223, s[4:5]
	s_add_i32 m0, s54, 0xc000
	s_nop 0
	global_load_lds_dwordx4 v224, s[4:5]
	s_add_u32 s4, s4, 0x20000
	s_addc_u32 s5, s5, 0
	s_add_i32 m0, s54, 0x2000
	s_nop 0
	global_load_lds_dwordx4 v222, s[0:1]
	s_add_u32 s0, s0, 0x20000
	s_addc_u32 s1, s1, 0
	global_load_dwordx4 v[144:147], v252, s[30:31] offset:0
	global_load_dwordx4 v[148:151], v252, s[30:31] offset:32
	global_load_dwordx4 v[152:155], v252, s[30:31] offset:64
	global_load_dwordx4 v[156:159], v252, s[30:31] offset:96
	s_add_i32 m0, s54, 0x4000
	s_nop 0
	global_load_lds_dwordx4 v222, s[0:1]
	s_add_u32 s0, s0, 0x20000
	s_addc_u32 s1, s1, 0
	v_mov_b64_e32 v[0:1], 0
	v_mov_b64_e32 v[2:3], 0
	v_mov_b64_e32 v[4:5], 0
	v_mov_b64_e32 v[6:7], 0
	v_mov_b64_e32 v[8:9], 0
	v_mov_b64_e32 v[10:11], 0
	v_mov_b64_e32 v[12:13], 0
	v_mov_b64_e32 v[14:15], 0
	v_mov_b64_e32 v[16:17], 0
	v_mov_b64_e32 v[18:19], 0
	v_mov_b64_e32 v[20:21], 0
	v_mov_b64_e32 v[22:23], 0
	v_mov_b64_e32 v[24:25], 0
	v_mov_b64_e32 v[26:27], 0
	v_mov_b64_e32 v[28:29], 0
	v_mov_b64_e32 v[30:31], 0
	v_mov_b64_e32 v[32:33], 0
	v_mov_b64_e32 v[34:35], 0
	v_mov_b64_e32 v[36:37], 0
	v_mov_b64_e32 v[38:39], 0
	v_mov_b64_e32 v[40:41], 0
	v_mov_b64_e32 v[42:43], 0
	v_mov_b64_e32 v[44:45], 0
	v_mov_b64_e32 v[46:47], 0
	v_mov_b64_e32 v[48:49], 0
	v_mov_b64_e32 v[50:51], 0
	v_mov_b64_e32 v[52:53], 0
	v_mov_b64_e32 v[54:55], 0
	v_mov_b64_e32 v[56:57], 0
	v_mov_b64_e32 v[58:59], 0
	v_mov_b64_e32 v[60:61], 0
	v_mov_b64_e32 v[62:63], 0
	s_waitcnt vmcnt(1) lgkmcnt(0)
	s_barrier
	ds_read_b128 v[176:179], v219 offset:0
	ds_read_b128 v[180:183], v219 offset:512
	ds_read_b128 v[184:187], v219 offset:2048
	ds_read_b128 v[188:191], v219 offset:2560
	ds_read_b128 v[192:195], v219 offset:4096
	ds_read_b128 v[196:199], v219 offset:4608
	ds_read_b128 v[200:203], v219 offset:6144
	ds_read_b128 v[206:209], v219 offset:6656
	s_waitcnt lgkmcnt(7)
	v_mfma_f32_32x32x16_bf16 v[80:95], v[176:179], v[144:147], 0
	s_waitcnt lgkmcnt(6)
	v_mfma_f32_32x32x16_bf16 v[96:111], v[180:183], v[144:147], 0
	s_waitcnt lgkmcnt(5)
	v_mfma_f32_32x32x16_bf16 v[80:95], v[184:187], v[148:151], v[80:95]
	s_waitcnt lgkmcnt(4)
	v_mfma_f32_32x32x16_bf16 v[96:111], v[188:191], v[148:151], v[96:111]
	s_waitcnt lgkmcnt(3)
	v_mfma_f32_32x32x16_bf16 v[80:95], v[192:195], v[152:155], v[80:95]
	s_waitcnt lgkmcnt(2)
	v_mfma_f32_32x32x16_bf16 v[96:111], v[196:199], v[152:155], v[96:111]
	s_waitcnt lgkmcnt(1)
	v_mfma_f32_32x32x16_bf16 v[80:95], v[200:203], v[156:159], v[80:95]
	s_waitcnt lgkmcnt(0)
	v_mfma_f32_32x32x16_bf16 v[96:111], v[206:209], v[156:159], v[96:111]
	s_nop 11
	s_cmp_lg_u32 s36, 0
	s_cbranch_scc1 .Lat_s0nomask_1
; #define WAIT_BAR(N) asm volatile("s_waitcnt vmcnt(" #N ") lgkmcnt(0)\n\ts_barrier":::"memory")
;   #define DMA_K(t,slot) glds16(ksrc+(long)(t)*KVBLK*DM,(unsigned)__builtin_amdgcn_readfirstlane(kdst+(slot)))
;   #define DMA_V(t,slot) glds16(vsrc+(long)(t)*KVBLK*DM,(unsigned)__builtin_amdgcn_readfirstlane(vdst+(slot)))
;   #define CMASK(P0,P1,t) do{int jb_=(t)-(NT-4); if(jb_>=0)cmask(P0,P1,jb_,qrel,hi);}while(0)
;   #define START(P0,P1) do{ const float rm=rowmax(P0,P1); resc=false; \
;     { const float dl=rm; mhat=fadd_s(mhat,dl); \
;       _Pragma("unroll") for(int r=0;r<16;++r){P0[r]=fsub_s(P0[r],dl);P1[r]=fsub_s(P1[r],dl);} \
;       _Pragma("unroll") for(int r=0;r<16;++r)negm[r]=-mhat; asm volatile("":"+v"(negm)); } \
;     _Pragma("unroll") for(int r=0;r<16;++r)P0[r]=__builtin_amdgcn_exp2f(P0[r]); }while(0)
;   #define ROT() do{sl_prev=sl_cur;sl_cur=sl_next;sl_next=(sl_next==(NSLOT-1)*SLOTB)?0:sl_next+SLOTB;}while(0)
;   #define CMASK(P0,P1,t) do{}while(0)
;   #define CMASK(P0,P1,t) do{int jb_=(t)-(NT-4); if(jb_>=0)cmask(P0,P1,jb_,qrel,hi);}while(0)
; __device__ __forceinline__ void cmask(f32x16&p0,f32x16&p1,int jb,int qrel,int hi){
;   const float NEG=-INFINITY; int kb=64*jb+4*hi;
;   #pragma unroll
;   for(int r=0;r<16;++r){int kv=kb+(r&3)+8*(r>>2); if(kv>qrel)p0[r]=NEG; if(kv+32>qrel)p1[r]=NEG;}
; }
; template<int THRL> __device__ __forceinline__ void attn_unit(int b,int qc,int vc,int qb,const bf16*Q,const bf16*__restrict__ K,const bf16*__restrict__ V,bf16*O,char*shm,const int tid){
;     ...
;   f32x16 pA0,pA1,pB0,pB1;
;   int sl_prev=0,sl_cur=0,sl_next=SLOTB;
;     ...
;   DMA_K(2,2*SLOTB);
;   WAIT_BAR(3);
;   qkt(pA0,pA1,Kbase,qr,negm,r32,hi);asm volatile("s_nop 15\n\ts_nop 7":"+v"(pA0),"+v"(pA1));CMASK(pA0,pA1,0);
;   START(pA0,pA1);
;   _Pragma("unroll") for(int r=0;r<16;++r)pA1[r]=__builtin_amdgcn_exp2f(pA1[r]);
;   WAIT_BAR(0);
;   DMA_K(3,0);DMA_V(1,SLOTB);
;   ROT();
;   kload8(kf,kp0+sl_cur);
;   WAIT_BAR(2);
	v_cmp_gt_i32_e64 s[28:29], 0, v225
	v_cmp_gt_i32_e64 s[30:31], 32, v225
	v_cmp_gt_i32_e64 s[34:35], 1, v225
	v_cndmask_b32_e64 v80, v80, v241, s[28:29]
	v_cmp_gt_i32_e64 s[28:29], 33, v225
	v_cndmask_b32_e64 v96, v96, v241, s[30:31]
	v_cmp_gt_i32_e64 s[30:31], 2, v225
	v_cndmask_b32_e64 v81, v81, v241, s[34:35]
	v_cmp_gt_i32_e64 s[34:35], 34, v225
	v_cndmask_b32_e64 v97, v97, v241, s[28:29]
	v_cmp_gt_i32_e64 s[28:29], 3, v225
	v_cndmask_b32_e64 v82, v82, v241, s[30:31]
	v_cmp_gt_i32_e64 s[30:31], 35, v225
	v_cndmask_b32_e64 v98, v98, v241, s[34:35]
	v_cmp_gt_i32_e64 s[34:35], 8, v225
	v_cndmask_b32_e64 v83, v83, v241, s[28:29]
	v_cmp_gt_i32_e64 s[28:29], 40, v225
	v_cndmask_b32_e64 v99, v99, v241, s[30:31]
	v_cmp_gt_i32_e64 s[30:31], 9, v225
	v_cndmask_b32_e64 v84, v84, v241, s[34:35]
	v_cmp_gt_i32_e64 s[34:35], 41, v225
	v_cndmask_b32_e64 v100, v100, v241, s[28:29]
	v_cmp_gt_i32_e64 s[28:29], 10, v225
	v_cndmask_b32_e64 v85, v85, v241, s[30:31]
	v_cmp_gt_i32_e64 s[30:31], 42, v225
	v_cndmask_b32_e64 v101, v101, v241, s[34:35]
	v_cmp_gt_i32_e64 s[34:35], 11, v225
	v_cndmask_b32_e64 v86, v86, v241, s[28:29]
	v_cmp_gt_i32_e64 s[28:29], 43, v225
	v_cndmask_b32_e64 v102, v102, v241, s[30:31]
	v_cmp_gt_i32_e64 s[30:31], 16, v225
	v_cndmask_b32_e64 v87, v87, v241, s[34:35]
	v_cmp_gt_i32_e64 s[34:35], 48, v225
	v_cndmask_b32_e64 v103, v103, v241, s[28:29]
	v_cmp_gt_i32_e64 s[28:29], 17, v225
	v_cndmask_b32_e64 v88, v88, v241, s[30:31]
	v_cmp_gt_i32_e64 s[30:31], 49, v225
	v_cndmask_b32_e64 v104, v104, v241, s[34:35]
	v_cmp_gt_i32_e64 s[34:35], 18, v225
	v_cndmask_b32_e64 v89, v89, v241, s[28:29]
	v_cmp_gt_i32_e64 s[28:29], 50, v225
	v_cndmask_b32_e64 v105, v105, v241, s[30:31]
	v_cmp_gt_i32_e64 s[30:31], 19, v225
	v_cndmask_b32_e64 v90, v90, v241, s[34:35]
	v_cmp_gt_i32_e64 s[34:35], 51, v225
	v_cndmask_b32_e64 v106, v106, v241, s[28:29]
	v_cmp_gt_i32_e64 s[28:29], 24, v225
	v_cndmask_b32_e64 v91, v91, v241, s[30:31]
	v_cmp_gt_i32_e64 s[30:31], 56, v225
	v_cndmask_b32_e64 v107, v107, v241, s[34:35]
	v_cmp_gt_i32_e64 s[34:35], 25, v225
	v_cndmask_b32_e64 v92, v92, v241, s[28:29]
	v_cmp_gt_i32_e64 s[28:29], 57, v225
	v_cndmask_b32_e64 v108, v108, v241, s[30:31]
	v_cmp_gt_i32_e64 s[30:31], 26, v225
	v_cndmask_b32_e64 v93, v93, v241, s[34:35]
	v_cmp_gt_i32_e64 s[34:35], 58, v225
	v_cndmask_b32_e64 v109, v109, v241, s[28:29]
	v_cmp_gt_i32_e64 s[28:29], 27, v225
	v_cndmask_b32_e64 v94, v94, v241, s[30:31]
	v_cmp_gt_i32_e64 s[30:31], 59, v225
	v_cndmask_b32_e64 v110, v110, v241, s[34:35]
	v_cndmask_b32_e64 v95, v95, v241, s[28:29]
	v_cndmask_b32_e64 v111, v111, v241, s[30:31]
.Lat_s0nomask_1:
	v_max3_f32 v246, v80, v81, v82
	v_max3_f32 v247, v83, v84, v85
	v_max3_f32 v246, v246, v86, v87
	v_max3_f32 v247, v247, v88, v89
	v_max3_f32 v246, v246, v90, v91
	v_max3_f32 v247, v247, v92, v93
	v_max3_f32 v246, v246, v94, v95
	v_max3_f32 v247, v247, v96, v97
	v_max3_f32 v246, v246, v98, v99
	v_max3_f32 v247, v247, v100, v101
	v_max3_f32 v246, v246, v102, v103
	v_max3_f32 v247, v247, v104, v105
	v_max3_f32 v246, v246, v106, v107
	v_max3_f32 v247, v247, v108, v109
	v_max3_f32 v246, v246, v110, v111
	v_max_f32_e32 v248, v246, v247
	v_mov_b32_e32 v246, v248
	s_nop 1
	v_permlane32_swap_b32_e32 v248, v246
	v_max_f32_e32 v248, v248, v246
	v_mov_b32_e32 v210, v248
	v_sub_f32_e32 v80, v80, v248
	v_sub_f32_e32 v81, v81, v248
	v_sub_f32_e32 v82, v82, v248
	v_sub_f32_e32 v83, v83, v248
	v_sub_f32_e32 v84, v84, v248
	v_sub_f32_e32 v85, v85, v248
	v_sub_f32_e32 v86, v86, v248
	v_sub_f32_e32 v87, v87, v248
	v_sub_f32_e32 v88, v88, v248
	v_sub_f32_e32 v89, v89, v248
	v_sub_f32_e32 v90, v90, v248
	v_sub_f32_e32 v91, v91, v248
	v_sub_f32_e32 v92, v92, v248
	v_sub_f32_e32 v93, v93, v248
	v_sub_f32_e32 v94, v94, v248
	v_sub_f32_e32 v95, v95, v248
	v_sub_f32_e32 v96, v96, v248
	v_sub_f32_e32 v97, v97, v248
	v_sub_f32_e32 v98, v98, v248
	v_sub_f32_e32 v99, v99, v248
	v_sub_f32_e32 v100, v100, v248
	v_sub_f32_e32 v101, v101, v248
	v_sub_f32_e32 v102, v102, v248
	v_sub_f32_e32 v103, v103, v248
	v_sub_f32_e32 v104, v104, v248
	v_sub_f32_e32 v105, v105, v248
	v_sub_f32_e32 v106, v106, v248
	v_sub_f32_e32 v107, v107, v248
	v_sub_f32_e32 v108, v108, v248
	v_sub_f32_e32 v109, v109, v248
	v_sub_f32_e32 v110, v110, v248
	v_sub_f32_e32 v111, v111, v248
	v_xor_b32_e32 v64, 0x80000000, v210
	v_mov_b32_e32 v65, v64
	v_mov_b32_e32 v66, v64
	v_mov_b32_e32 v67, v64
	v_mov_b32_e32 v68, v64
	v_mov_b32_e32 v69, v64
	v_mov_b32_e32 v70, v64
	v_mov_b32_e32 v71, v64
	v_mov_b32_e32 v72, v64
	v_mov_b32_e32 v73, v64
	v_mov_b32_e32 v74, v64
	v_mov_b32_e32 v75, v64
	v_mov_b32_e32 v76, v64
	v_mov_b32_e32 v77, v64
	v_mov_b32_e32 v78, v64
	v_mov_b32_e32 v79, v64
	s_waitcnt vmcnt(0) lgkmcnt(0)
	s_barrier
	s_mov_b32 m0, s54
	s_nop 0
	global_load_lds_dwordx4 v222, s[0:1]
	s_add_u32 s0, s0, 0x20000
	s_addc_u32 s1, s1, 0
	s_add_i32 m0, s54, 0x8000
	s_nop 0
	global_load_lds_dwordx4 v223, s[4:5]
	s_add_i32 m0, s54, 0xe000
	s_nop 0
	global_load_lds_dwordx4 v224, s[4:5]
	s_add_u32 s4, s4, 0x20000
	s_addc_u32 s5, s5, 0
	ds_read_b128 v[176:179], v219 offset:8192
	ds_read_b128 v[180:183], v219 offset:8704
	ds_read_b128 v[184:187], v219 offset:10240
	ds_read_b128 v[188:191], v219 offset:10752
	ds_read_b128 v[192:195], v219 offset:12288
	ds_read_b128 v[196:199], v219 offset:12800
	ds_read_b128 v[200:203], v219 offset:14336
	ds_read_b128 v[206:209], v219 offset:14848
	v_exp_f32_e32 v80, v80
	v_exp_f32_e32 v81, v81
	v_exp_f32_e32 v82, v82
	v_exp_f32_e32 v83, v83
	v_exp_f32_e32 v84, v84
	v_exp_f32_e32 v85, v85
	v_exp_f32_e32 v86, v86
	v_exp_f32_e32 v87, v87
	v_exp_f32_e32 v88, v88
	v_exp_f32_e32 v89, v89
	v_exp_f32_e32 v90, v90
	v_exp_f32_e32 v91, v91
	v_exp_f32_e32 v92, v92
	v_exp_f32_e32 v93, v93
	v_exp_f32_e32 v94, v94
	v_exp_f32_e32 v95, v95
	v_exp_f32_e32 v96, v96
	v_exp_f32_e32 v97, v97
	v_exp_f32_e32 v98, v98
	v_exp_f32_e32 v99, v99
	v_exp_f32_e32 v100, v100
	v_exp_f32_e32 v101, v101
	v_exp_f32_e32 v102, v102
	v_exp_f32_e32 v103, v103
	v_exp_f32_e32 v104, v104
	v_exp_f32_e32 v105, v105
	v_exp_f32_e32 v106, v106
	v_exp_f32_e32 v107, v107
	v_exp_f32_e32 v108, v108
	v_exp_f32_e32 v109, v109
	v_exp_f32_e32 v110, v110
	v_exp_f32_e32 v111, v111
	s_waitcnt vmcnt(3) lgkmcnt(0)
	s_barrier
	s_mov_b32 s16, 0
	s_movk_i32 s17, 0x2000
	s_movk_i32 s18, 0x4000
	s_cmp_eq_u32 s36, 0
	s_cbranch_scc1 .Lat_step_T3
	s_lshl_b32 s20, s36, 1
	s_add_i32 s20, s20, -1
.Lat_mainloop:
.Lat_step_M1:
	v_add_u32_e32 v243, s16, v204
	ds_read_b64_tr_b16 v[214:215], v243 offset:24576
	ds_read_b64_tr_b16 v[216:217], v243 offset:25088
	v_mfma_f32_32x32x16_bf16 v[112:127], v[176:179], v[144:147], v[64:79]
	v_add_f32_e32 v245, v80, v81
	v_add_f32_e32 v245, v82, v245
	v_add_f32_e32 v245, v83, v245
	v_add_f32_e32 v245, v84, v245
	v_add_f32_e32 v245, v85, v245
	v_cvt_pk_bf16_f32 v160, v80, v81
	v_cvt_pk_bf16_f32 v161, v82, v83
	ds_read_b64_tr_b16 v[80:81], v243 offset:28672
	ds_read_b64_tr_b16 v[82:83], v243 offset:29184
	v_mfma_f32_32x32x16_bf16 v[128:143], v[180:183], v[144:147], v[64:79]
	v_add_f32_e32 v245, v86, v245
	v_add_f32_e32 v245, v87, v245
	v_add_f32_e32 v245, v88, v245
	v_add_f32_e32 v245, v89, v245
	v_cvt_pk_bf16_f32 v162, v84, v85
	v_cvt_pk_bf16_f32 v163, v86, v87
	ds_read_b64_tr_b16 v[84:85], v243 offset:25600
	ds_read_b64_tr_b16 v[86:87], v243 offset:26112
	v_mfma_f32_32x32x16_bf16 v[112:127], v[184:187], v[148:151], v[112:127]
	v_add_f32_e32 v245, v90, v245
	v_add_f32_e32 v245, v91, v245
	v_add_f32_e32 v245, v92, v245
	v_add_f32_e32 v245, v93, v245
	v_cvt_pk_bf16_f32 v164, v88, v89
	v_cvt_pk_bf16_f32 v165, v90, v91
	ds_read_b64_tr_b16 v[88:89], v243 offset:29696
	ds_read_b64_tr_b16 v[90:91], v243 offset:30208
	v_mfma_f32_32x32x16_bf16 v[128:143], v[188:191], v[148:151], v[128:143]
	v_add_f32_e32 v245, v94, v245
	v_add_f32_e32 v245, v95, v245
	v_add_f32_e32 v245, v96, v245
	v_add_f32_e32 v245, v97, v245
	v_cvt_pk_bf16_f32 v166, v92, v93
	v_cvt_pk_bf16_f32 v167, v94, v95
	ds_read_b64_tr_b16 v[92:93], v243 offset:26624
	ds_read_b64_tr_b16 v[94:95], v243 offset:27136
	v_mfma_f32_32x32x16_bf16 v[112:127], v[192:195], v[152:155], v[112:127]
	v_add_f32_e32 v245, v98, v245
	v_add_f32_e32 v245, v99, v245
	v_add_f32_e32 v245, v100, v245
	v_add_f32_e32 v245, v101, v245
	v_cvt_pk_bf16_f32 v168, v96, v97
	v_cvt_pk_bf16_f32 v169, v98, v99
	ds_read_b64_tr_b16 v[96:97], v243 offset:30720
	ds_read_b64_tr_b16 v[98:99], v243 offset:31232
	v_mfma_f32_32x32x16_bf16 v[128:143], v[196:199], v[152:155], v[128:143]
	v_add_f32_e32 v245, v102, v245
	v_add_f32_e32 v245, v103, v245
	v_add_f32_e32 v245, v104, v245
	v_add_f32_e32 v245, v105, v245
	v_cvt_pk_bf16_f32 v170, v100, v101
	v_cvt_pk_bf16_f32 v171, v102, v103
	ds_read_b64_tr_b16 v[100:101], v243 offset:27648
	ds_read_b64_tr_b16 v[102:103], v243 offset:28160
	v_mfma_f32_32x32x16_bf16 v[112:127], v[200:203], v[156:159], v[112:127]
	v_add_f32_e32 v245, v106, v245
	v_add_f32_e32 v245, v107, v245
	v_add_f32_e32 v245, v108, v245
	v_add_f32_e32 v245, v109, v245
	v_cvt_pk_bf16_f32 v172, v104, v105
	v_cvt_pk_bf16_f32 v173, v106, v107
	s_waitcnt lgkmcnt(12)
	ds_read_b64_tr_b16 v[104:105], v243 offset:31744
	ds_read_b64_tr_b16 v[106:107], v243 offset:32256
	v_mfma_f32_32x32x16_bf16 v[128:143], v[206:209], v[156:159], v[128:143]
	v_add_f32_e32 v245, v110, v245
	v_add_f32_e32 v245, v111, v245
	v_cvt_pk_bf16_f32 v174, v108, v109
	v_cvt_pk_bf16_f32 v175, v110, v111
	v_add_f32_e32 v211, v211, v245
	s_add_i32 m0, s17, s54
	s_nop 0
	global_load_lds_dwordx4 v222, s[0:1]
	s_add_u32 s0, s0, 0x20000
	s_addc_u32 s1, s1, 0
	s_add_i32 s21, s18, s54
	s_add_i32 m0, s21, 0x6000
	s_nop 0
	global_load_lds_dwordx4 v223, s[4:5]
	s_add_i32 m0, s21, 0xc000
	s_nop 0
	global_load_lds_dwordx4 v224, s[4:5]
	s_add_u32 s4, s4, 0x20000
	s_addc_u32 s5, s5, 0
	v_max3_f32 v246, v112, v113, v114
	v_max3_f32 v247, v115, v116, v117
	v_max3_f32 v246, v246, v118, v119
	v_max3_f32 v247, v247, v120, v121
	v_max3_f32 v246, v246, v122, v123
	v_max3_f32 v247, v247, v124, v125
	v_max3_f32 v246, v246, v126, v127
	v_max3_f32 v247, v247, v128, v129
	v_max3_f32 v246, v246, v130, v131
	v_max3_f32 v247, v247, v132, v133
	v_max3_f32 v246, v246, v134, v135
	v_max3_f32 v247, v247, v136, v137
	v_max3_f32 v246, v246, v138, v139
	v_max3_f32 v247, v247, v140, v141
	v_max3_f32 v246, v246, v142, v143
	v_max_f32_e32 v248, v246, v247
	v_mov_b32_e32 v246, v248
	s_nop 1
	v_permlane32_swap_b32_e32 v248, v246
	v_max_f32_e32 v248, v248, v246
	s_mov_b32 s26, 0
	v_cmp_lt_f32_e32 vcc, s87, v248
	s_cmp_lg_u64 vcc, 0
	s_cbranch_scc1 .Lat_rare_M1
.Lat_cont_M1:
	v_add_u32_e32 v244, s18, v219
	v_mfma_f32_32x32x16_bf16 v[0:15], v[160:163], v[214:217], v[0:15]
	v_exp_f32_e32 v112, v112
	v_exp_f32_e32 v113, v113
	s_waitcnt lgkmcnt(12)
	ds_read_b64_tr_b16 v[214:215], v243 offset:49152
	ds_read_b64_tr_b16 v[216:217], v243 offset:49664
	v_mfma_f32_32x32x16_bf16 v[16:31], v[160:163], v[80:83], v[16:31]
	v_exp_f32_e32 v114, v114
	v_exp_f32_e32 v115, v115
	s_waitcnt lgkmcnt(12)
	ds_read_b64_tr_b16 v[80:81], v243 offset:53248
	ds_read_b64_tr_b16 v[82:83], v243 offset:53760
	v_mfma_f32_32x32x16_bf16 v[0:15], v[164:167], v[84:87], v[0:15]
	v_exp_f32_e32 v116, v116
	v_exp_f32_e32 v117, v117
	s_waitcnt lgkmcnt(12)
	ds_read_b64_tr_b16 v[84:85], v243 offset:50176
	ds_read_b64_tr_b16 v[86:87], v243 offset:50688
	v_mfma_f32_32x32x16_bf16 v[16:31], v[164:167], v[88:91], v[16:31]
	v_exp_f32_e32 v118, v118
	v_exp_f32_e32 v119, v119
	s_waitcnt lgkmcnt(12)
	ds_read_b64_tr_b16 v[88:89], v243 offset:54272
	ds_read_b64_tr_b16 v[90:91], v243 offset:54784
	v_mfma_f32_32x32x16_bf16 v[0:15], v[168:171], v[92:95], v[0:15]
	v_exp_f32_e32 v120, v120
	v_exp_f32_e32 v121, v121
	s_waitcnt lgkmcnt(12)
	ds_read_b64_tr_b16 v[92:93], v243 offset:51200
	ds_read_b64_tr_b16 v[94:95], v243 offset:51712
	v_mfma_f32_32x32x16_bf16 v[16:31], v[168:171], v[96:99], v[16:31]
	v_exp_f32_e32 v122, v122
	v_exp_f32_e32 v123, v123
	s_waitcnt lgkmcnt(12)
	ds_read_b64_tr_b16 v[96:97], v243 offset:55296
	ds_read_b64_tr_b16 v[98:99], v243 offset:55808
	v_mfma_f32_32x32x16_bf16 v[0:15], v[172:175], v[100:103], v[0:15]
	v_exp_f32_e32 v124, v124
	v_exp_f32_e32 v125, v125
	s_waitcnt lgkmcnt(12)
; #define WAIT_BAR(N) asm volatile("s_waitcnt vmcnt(" #N ") lgkmcnt(0)\n\ts_barrier":::"memory")
;   #define RESC() do{ if(resc){ asm volatile("s_waitcnt lgkmcnt(0)":::"memory"); \
;       _Pragma("unroll") for(int d_=0;d_<2;++d_) _Pragma("unroll") for(int r=0;r<16;++r)o[d_][r]*=wsf[crow(r,hi)]; } }while(0)
;   #define ROT() do{sl_prev=sl_cur;sl_cur=sl_next;sl_next=(sl_next==(NSLOT-1)*SLOTB)?0:sl_next+SLOTB;}while(0)
; template<int THRL> __device__ __forceinline__ void attn_unit(int b,int qc,int vc,int qb,const bf16*Q,const bf16*__restrict__ K,const bf16*__restrict__ V,bf16*O,char*shm,const int tid){
;     ...
;   int t=1;
;     ...
;   for(;t+5<NT;t+=2){
;     STEP(pB0,pB1,pA0,pA1,t,true,true,true);     WAIT_BAR(2); RESC(); ROT();
;     STEP(pA0,pA1,pB0,pB1,t+1,true,true,true);   WAIT_BAR(2); RESC(); ROT();
	ds_read_b64_tr_b16 v[100:101], v243 offset:52224
	ds_read_b64_tr_b16 v[102:103], v243 offset:52736
	v_mfma_f32_32x32x16_bf16 v[16:31], v[172:175], v[104:107], v[16:31]
	v_exp_f32_e32 v126, v126
	v_exp_f32_e32 v127, v127
	s_waitcnt lgkmcnt(12)
	ds_read_b64_tr_b16 v[104:105], v243 offset:56320
	ds_read_b64_tr_b16 v[106:107], v243 offset:56832
	v_mfma_f32_32x32x16_bf16 v[32:47], v[160:163], v[214:217], v[32:47]
	v_exp_f32_e32 v128, v128
	v_exp_f32_e32 v129, v129
	s_waitcnt lgkmcnt(12)
	ds_read_b128 v[176:179], v244 offset:0
	ds_read_b128 v[180:183], v244 offset:512
	v_mfma_f32_32x32x16_bf16 v[48:63], v[160:163], v[80:83], v[48:63]
	v_exp_f32_e32 v130, v130
	v_exp_f32_e32 v131, v131
	s_waitcnt lgkmcnt(12)
	ds_read_b128 v[184:187], v244 offset:2048
	ds_read_b128 v[188:191], v244 offset:2560
	v_mfma_f32_32x32x16_bf16 v[32:47], v[164:167], v[84:87], v[32:47]
	v_exp_f32_e32 v132, v132
	v_exp_f32_e32 v133, v133
	s_waitcnt lgkmcnt(12)
	ds_read_b128 v[192:195], v244 offset:4096
	ds_read_b128 v[196:199], v244 offset:4608
	v_mfma_f32_32x32x16_bf16 v[48:63], v[164:167], v[88:91], v[48:63]
	v_exp_f32_e32 v134, v134
	v_exp_f32_e32 v135, v135
	s_waitcnt lgkmcnt(12)
	ds_read_b128 v[200:203], v244 offset:6144
	ds_read_b128 v[206:209], v244 offset:6656
	v_mfma_f32_32x32x16_bf16 v[32:47], v[168:171], v[92:95], v[32:47]
	v_exp_f32_e32 v136, v136
	v_exp_f32_e32 v137, v137
	s_waitcnt lgkmcnt(12)
	v_mfma_f32_32x32x16_bf16 v[48:63], v[168:171], v[96:99], v[48:63]
	v_exp_f32_e32 v138, v138
	v_exp_f32_e32 v139, v139
	s_waitcnt lgkmcnt(10)
	v_mfma_f32_32x32x16_bf16 v[32:47], v[172:175], v[100:103], v[32:47]
	v_exp_f32_e32 v140, v140
	v_exp_f32_e32 v141, v141
	s_waitcnt lgkmcnt(8)
	v_mfma_f32_32x32x16_bf16 v[48:63], v[172:175], v[104:107], v[48:63]
	v_exp_f32_e32 v142, v142
	v_exp_f32_e32 v143, v143
	s_waitcnt vmcnt(3) lgkmcnt(0)
	s_barrier
	s_cmp_eq_u32 s26, 0
	s_cbranch_scc1 .Lat_noresc_M1
	s_waitcnt lgkmcnt(0)
	ds_read_b128 v[214:217], v227 offset:0
	s_waitcnt lgkmcnt(0)
	v_pk_mul_f32 v[0:1], v[0:1], v[214:215]
	v_pk_mul_f32 v[2:3], v[2:3], v[216:217]
	v_pk_mul_f32 v[16:17], v[16:17], v[214:215]
	v_pk_mul_f32 v[18:19], v[18:19], v[216:217]
	v_pk_mul_f32 v[32:33], v[32:33], v[214:215]
	v_pk_mul_f32 v[34:35], v[34:35], v[216:217]
	v_pk_mul_f32 v[48:49], v[48:49], v[214:215]
	v_pk_mul_f32 v[50:51], v[50:51], v[216:217]
	ds_read_b128 v[214:217], v227 offset:32
	s_waitcnt lgkmcnt(0)
	v_pk_mul_f32 v[4:5], v[4:5], v[214:215]
	v_pk_mul_f32 v[6:7], v[6:7], v[216:217]
	v_pk_mul_f32 v[20:21], v[20:21], v[214:215]
	v_pk_mul_f32 v[22:23], v[22:23], v[216:217]
	v_pk_mul_f32 v[36:37], v[36:37], v[214:215]
	v_pk_mul_f32 v[38:39], v[38:39], v[216:217]
	v_pk_mul_f32 v[52:53], v[52:53], v[214:215]
	v_pk_mul_f32 v[54:55], v[54:55], v[216:217]
	ds_read_b128 v[214:217], v227 offset:64
	s_waitcnt lgkmcnt(0)
	v_pk_mul_f32 v[8:9], v[8:9], v[214:215]
	v_pk_mul_f32 v[10:11], v[10:11], v[216:217]
	v_pk_mul_f32 v[24:25], v[24:25], v[214:215]
	v_pk_mul_f32 v[26:27], v[26:27], v[216:217]
	v_pk_mul_f32 v[40:41], v[40:41], v[214:215]
	v_pk_mul_f32 v[42:43], v[42:43], v[216:217]
	v_pk_mul_f32 v[56:57], v[56:57], v[214:215]
	v_pk_mul_f32 v[58:59], v[58:59], v[216:217]
	ds_read_b128 v[214:217], v227 offset:96
	s_waitcnt lgkmcnt(0)
	v_pk_mul_f32 v[12:13], v[12:13], v[214:215]
	v_pk_mul_f32 v[14:15], v[14:15], v[216:217]
	v_pk_mul_f32 v[28:29], v[28:29], v[214:215]
	v_pk_mul_f32 v[30:31], v[30:31], v[216:217]
	v_pk_mul_f32 v[44:45], v[44:45], v[214:215]
	v_pk_mul_f32 v[46:47], v[46:47], v[216:217]
	v_pk_mul_f32 v[60:61], v[60:61], v[214:215]
	v_pk_mul_f32 v[62:63], v[62:63], v[216:217]
.Lat_noresc_M1:
	s_mov_b32 s21, s16
	s_mov_b32 s16, s17
	s_mov_b32 s17, s18
	s_mov_b32 s18, s21
.Lat_step_M2:
	v_add_u32_e32 v243, s16, v204
	ds_read_b64_tr_b16 v[214:215], v243 offset:24576
	ds_read_b64_tr_b16 v[216:217], v243 offset:25088
	v_mfma_f32_32x32x16_bf16 v[80:95], v[176:179], v[144:147], v[64:79]
	v_add_f32_e32 v245, v112, v113
	v_add_f32_e32 v245, v114, v245
	v_add_f32_e32 v245, v115, v245
	v_add_f32_e32 v245, v116, v245
	v_add_f32_e32 v245, v117, v245
	v_cvt_pk_bf16_f32 v160, v112, v113
	v_cvt_pk_bf16_f32 v161, v114, v115
	ds_read_b64_tr_b16 v[112:113], v243 offset:28672
	ds_read_b64_tr_b16 v[114:115], v243 offset:29184
	v_mfma_f32_32x32x16_bf16 v[96:111], v[180:183], v[144:147], v[64:79]
	v_add_f32_e32 v245, v118, v245
	v_add_f32_e32 v245, v119, v245
	v_add_f32_e32 v245, v120, v245
	v_add_f32_e32 v245, v121, v245
	v_cvt_pk_bf16_f32 v162, v116, v117
	v_cvt_pk_bf16_f32 v163, v118, v119
	ds_read_b64_tr_b16 v[116:117], v243 offset:25600
	ds_read_b64_tr_b16 v[118:119], v243 offset:26112
	v_mfma_f32_32x32x16_bf16 v[80:95], v[184:187], v[148:151], v[80:95]
	v_add_f32_e32 v245, v122, v245
	v_add_f32_e32 v245, v123, v245
	v_add_f32_e32 v245, v124, v245
	v_add_f32_e32 v245, v125, v245
	v_cvt_pk_bf16_f32 v164, v120, v121
	v_cvt_pk_bf16_f32 v165, v122, v123
	ds_read_b64_tr_b16 v[120:121], v243 offset:29696
	ds_read_b64_tr_b16 v[122:123], v243 offset:30208
	v_mfma_f32_32x32x16_bf16 v[96:111], v[188:191], v[148:151], v[96:111]
	v_add_f32_e32 v245, v126, v245
	v_add_f32_e32 v245, v127, v245
	v_add_f32_e32 v245, v128, v245
	v_add_f32_e32 v245, v129, v245
	v_cvt_pk_bf16_f32 v166, v124, v125
	v_cvt_pk_bf16_f32 v167, v126, v127
	ds_read_b64_tr_b16 v[124:125], v243 offset:26624
	ds_read_b64_tr_b16 v[126:127], v243 offset:27136
	v_mfma_f32_32x32x16_bf16 v[80:95], v[192:195], v[152:155], v[80:95]
	v_add_f32_e32 v245, v130, v245
	v_add_f32_e32 v245, v131, v245
	v_add_f32_e32 v245, v132, v245
	v_add_f32_e32 v245, v133, v245
	v_cvt_pk_bf16_f32 v168, v128, v129
	v_cvt_pk_bf16_f32 v169, v130, v131
	ds_read_b64_tr_b16 v[128:129], v243 offset:30720
	ds_read_b64_tr_b16 v[130:131], v243 offset:31232
	v_mfma_f32_32x32x16_bf16 v[96:111], v[196:199], v[152:155], v[96:111]
	v_add_f32_e32 v245, v134, v245
	v_add_f32_e32 v245, v135, v245
	v_add_f32_e32 v245, v136, v245
	v_add_f32_e32 v245, v137, v245
	v_cvt_pk_bf16_f32 v170, v132, v133
	v_cvt_pk_bf16_f32 v171, v134, v135
	ds_read_b64_tr_b16 v[132:133], v243 offset:27648
	ds_read_b64_tr_b16 v[134:135], v243 offset:28160
	v_mfma_f32_32x32x16_bf16 v[80:95], v[200:203], v[156:159], v[80:95]
	v_add_f32_e32 v245, v138, v245
	v_add_f32_e32 v245, v139, v245
	v_add_f32_e32 v245, v140, v245
	v_add_f32_e32 v245, v141, v245
	v_cvt_pk_bf16_f32 v172, v136, v137
	v_cvt_pk_bf16_f32 v173, v138, v139
	s_waitcnt lgkmcnt(12)
; #define WAIT_BAR(N) asm volatile("s_waitcnt vmcnt(" #N ") lgkmcnt(0)\n\ts_barrier":::"memory")
;   #define RESC() do{ if(resc){ asm volatile("s_waitcnt lgkmcnt(0)":::"memory"); \
;       _Pragma("unroll") for(int d_=0;d_<2;++d_) _Pragma("unroll") for(int r=0;r<16;++r)o[d_][r]*=wsf[crow(r,hi)]; } }while(0)
;   #define ROT() do{sl_prev=sl_cur;sl_cur=sl_next;sl_next=(sl_next==(NSLOT-1)*SLOTB)?0:sl_next+SLOTB;}while(0)
; template<int THRL> __device__ __forceinline__ void attn_unit(int b,int qc,int vc,int qb,const bf16*Q,const bf16*__restrict__ K,const bf16*__restrict__ V,bf16*O,char*shm,const int tid){
;     ...
;   int t=1;
;     ...
;   for(;t+5<NT;t+=2){
;     STEP(pB0,pB1,pA0,pA1,t,true,true,true);     WAIT_BAR(2); RESC(); ROT();
;     STEP(pA0,pA1,pB0,pB1,t+1,true,true,true);   WAIT_BAR(2); RESC(); ROT();
	ds_read_b64_tr_b16 v[136:137], v243 offset:31744
	ds_read_b64_tr_b16 v[138:139], v243 offset:32256
	v_mfma_f32_32x32x16_bf16 v[96:111], v[206:209], v[156:159], v[96:111]
	v_add_f32_e32 v245, v142, v245
	v_add_f32_e32 v245, v143, v245
	v_cvt_pk_bf16_f32 v174, v140, v141
	v_cvt_pk_bf16_f32 v175, v142, v143
	v_add_f32_e32 v211, v211, v245
	s_add_i32 m0, s17, s54
	s_nop 0
	global_load_lds_dwordx4 v222, s[0:1]
	s_add_u32 s0, s0, 0x20000
	s_addc_u32 s1, s1, 0
	s_add_i32 s21, s18, s54
	s_add_i32 m0, s21, 0x6000
	s_nop 0
	global_load_lds_dwordx4 v223, s[4:5]
	s_add_i32 m0, s21, 0xc000
	s_nop 0
	global_load_lds_dwordx4 v224, s[4:5]
	s_add_u32 s4, s4, 0x20000
	s_addc_u32 s5, s5, 0
	v_max3_f32 v246, v80, v81, v82
	v_max3_f32 v247, v83, v84, v85
	v_max3_f32 v246, v246, v86, v87
	v_max3_f32 v247, v247, v88, v89
	v_max3_f32 v246, v246, v90, v91
	v_max3_f32 v247, v247, v92, v93
	v_max3_f32 v246, v246, v94, v95
	v_max3_f32 v247, v247, v96, v97
	v_max3_f32 v246, v246, v98, v99
	v_max3_f32 v247, v247, v100, v101
	v_max3_f32 v246, v246, v102, v103
	v_max3_f32 v247, v247, v104, v105
	v_max3_f32 v246, v246, v106, v107
	v_max3_f32 v247, v247, v108, v109
	v_max3_f32 v246, v246, v110, v111
	v_max_f32_e32 v248, v246, v247
	v_mov_b32_e32 v246, v248
	s_nop 1
	v_permlane32_swap_b32_e32 v248, v246
	v_max_f32_e32 v248, v248, v246
	s_mov_b32 s26, 0
	v_cmp_lt_f32_e32 vcc, s87, v248
	s_cmp_lg_u64 vcc, 0
	s_cbranch_scc1 .Lat_rare_M2
.Lat_cont_M2:
	v_add_u32_e32 v244, s18, v219
	v_mfma_f32_32x32x16_bf16 v[0:15], v[160:163], v[214:217], v[0:15]
	v_exp_f32_e32 v80, v80
	v_exp_f32_e32 v81, v81
	s_waitcnt lgkmcnt(12)
	ds_read_b64_tr_b16 v[214:215], v243 offset:49152
	ds_read_b64_tr_b16 v[216:217], v243 offset:49664
	v_mfma_f32_32x32x16_bf16 v[16:31], v[160:163], v[112:115], v[16:31]
	v_exp_f32_e32 v82, v82
	v_exp_f32_e32 v83, v83
	s_waitcnt lgkmcnt(12)
	ds_read_b64_tr_b16 v[112:113], v243 offset:53248
	ds_read_b64_tr_b16 v[114:115], v243 offset:53760
	v_mfma_f32_32x32x16_bf16 v[0:15], v[164:167], v[116:119], v[0:15]
	v_exp_f32_e32 v84, v84
	v_exp_f32_e32 v85, v85
	s_waitcnt lgkmcnt(12)
	ds_read_b64_tr_b16 v[116:117], v243 offset:50176
	ds_read_b64_tr_b16 v[118:119], v243 offset:50688
	v_mfma_f32_32x32x16_bf16 v[16:31], v[164:167], v[120:123], v[16:31]
	v_exp_f32_e32 v86, v86
	v_exp_f32_e32 v87, v87
	s_waitcnt lgkmcnt(12)
	ds_read_b64_tr_b16 v[120:121], v243 offset:54272
	ds_read_b64_tr_b16 v[122:123], v243 offset:54784
	v_mfma_f32_32x32x16_bf16 v[0:15], v[168:171], v[124:127], v[0:15]
	v_exp_f32_e32 v88, v88
	v_exp_f32_e32 v89, v89
	s_waitcnt lgkmcnt(12)
	ds_read_b64_tr_b16 v[124:125], v243 offset:51200
	ds_read_b64_tr_b16 v[126:127], v243 offset:51712
	v_mfma_f32_32x32x16_bf16 v[16:31], v[168:171], v[128:131], v[16:31]
	v_exp_f32_e32 v90, v90
	v_exp_f32_e32 v91, v91
	s_waitcnt lgkmcnt(12)
	ds_read_b64_tr_b16 v[128:129], v243 offset:55296
	ds_read_b64_tr_b16 v[130:131], v243 offset:55808
	v_mfma_f32_32x32x16_bf16 v[0:15], v[172:175], v[132:135], v[0:15]
	v_exp_f32_e32 v92, v92
	v_exp_f32_e32 v93, v93
	s_waitcnt lgkmcnt(12)
	ds_read_b64_tr_b16 v[132:133], v243 offset:52224
	ds_read_b64_tr_b16 v[134:135], v243 offset:52736
	v_mfma_f32_32x32x16_bf16 v[16:31], v[172:175], v[136:139], v[16:31]
	v_exp_f32_e32 v94, v94
	v_exp_f32_e32 v95, v95
	s_waitcnt lgkmcnt(12)
	ds_read_b64_tr_b16 v[136:137], v243 offset:56320
	ds_read_b64_tr_b16 v[138:139], v243 offset:56832
	v_mfma_f32_32x32x16_bf16 v[32:47], v[160:163], v[214:217], v[32:47]
	v_exp_f32_e32 v96, v96
	v_exp_f32_e32 v97, v97
	s_waitcnt lgkmcnt(12)
	ds_read_b128 v[176:179], v244 offset:0
	ds_read_b128 v[180:183], v244 offset:512
	v_mfma_f32_32x32x16_bf16 v[48:63], v[160:163], v[112:115], v[48:63]
	v_exp_f32_e32 v98, v98
	v_exp_f32_e32 v99, v99
	s_waitcnt lgkmcnt(12)
	ds_read_b128 v[184:187], v244 offset:2048
	ds_read_b128 v[188:191], v244 offset:2560
	v_mfma_f32_32x32x16_bf16 v[32:47], v[164:167], v[116:119], v[32:47]
	v_exp_f32_e32 v100, v100
	v_exp_f32_e32 v101, v101
	s_waitcnt lgkmcnt(12)
	ds_read_b128 v[192:195], v244 offset:4096
	ds_read_b128 v[196:199], v244 offset:4608
	v_mfma_f32_32x32x16_bf16 v[48:63], v[164:167], v[120:123], v[48:63]
	v_exp_f32_e32 v102, v102
	v_exp_f32_e32 v103, v103
	s_waitcnt lgkmcnt(12)
	ds_read_b128 v[200:203], v244 offset:6144
	ds_read_b128 v[206:209], v244 offset:6656
	v_mfma_f32_32x32x16_bf16 v[32:47], v[168:171], v[124:127], v[32:47]
	v_exp_f32_e32 v104, v104
	v_exp_f32_e32 v105, v105
	s_waitcnt lgkmcnt(12)
	v_mfma_f32_32x32x16_bf16 v[48:63], v[168:171], v[128:131], v[48:63]
	v_exp_f32_e32 v106, v106
	v_exp_f32_e32 v107, v107
	s_waitcnt lgkmcnt(10)
	v_mfma_f32_32x32x16_bf16 v[32:47], v[172:175], v[132:135], v[32:47]
	v_exp_f32_e32 v108, v108
	v_exp_f32_e32 v109, v109
	s_waitcnt lgkmcnt(8)
	v_mfma_f32_32x32x16_bf16 v[48:63], v[172:175], v[136:139], v[48:63]
	v_exp_f32_e32 v110, v110
	v_exp_f32_e32 v111, v111
	s_waitcnt vmcnt(3) lgkmcnt(0)
	s_barrier
	s_cmp_eq_u32 s26, 0
	s_cbranch_scc1 .Lat_noresc_M2
	s_waitcnt lgkmcnt(0)
	ds_read_b128 v[214:217], v227 offset:0
	s_waitcnt lgkmcnt(0)
	v_pk_mul_f32 v[0:1], v[0:1], v[214:215]
	v_pk_mul_f32 v[2:3], v[2:3], v[216:217]
	v_pk_mul_f32 v[16:17], v[16:17], v[214:215]
	v_pk_mul_f32 v[18:19], v[18:19], v[216:217]
	v_pk_mul_f32 v[32:33], v[32:33], v[214:215]
	v_pk_mul_f32 v[34:35], v[34:35], v[216:217]
	v_pk_mul_f32 v[48:49], v[48:49], v[214:215]
	v_pk_mul_f32 v[50:51], v[50:51], v[216:217]
	ds_read_b128 v[214:217], v227 offset:32
	s_waitcnt lgkmcnt(0)
	v_pk_mul_f32 v[4:5], v[4:5], v[214:215]
	v_pk_mul_f32 v[6:7], v[6:7], v[216:217]
	v_pk_mul_f32 v[20:21], v[20:21], v[214:215]
	v_pk_mul_f32 v[22:23], v[22:23], v[216:217]
	v_pk_mul_f32 v[36:37], v[36:37], v[214:215]
	v_pk_mul_f32 v[38:39], v[38:39], v[216:217]
	v_pk_mul_f32 v[52:53], v[52:53], v[214:215]
	v_pk_mul_f32 v[54:55], v[54:55], v[216:217]
	ds_read_b128 v[214:217], v227 offset:64
	s_waitcnt lgkmcnt(0)
	v_pk_mul_f32 v[8:9], v[8:9], v[214:215]
	v_pk_mul_f32 v[10:11], v[10:11], v[216:217]
	v_pk_mul_f32 v[24:25], v[24:25], v[214:215]
	v_pk_mul_f32 v[26:27], v[26:27], v[216:217]
	v_pk_mul_f32 v[40:41], v[40:41], v[214:215]
	v_pk_mul_f32 v[42:43], v[42:43], v[216:217]
	v_pk_mul_f32 v[56:57], v[56:57], v[214:215]
	v_pk_mul_f32 v[58:59], v[58:59], v[216:217]
	ds_read_b128 v[214:217], v227 offset:96
	s_waitcnt lgkmcnt(0)
	v_pk_mul_f32 v[12:13], v[12:13], v[214:215]
	v_pk_mul_f32 v[14:15], v[14:15], v[216:217]
	v_pk_mul_f32 v[28:29], v[28:29], v[214:215]
	v_pk_mul_f32 v[30:31], v[30:31], v[216:217]
	v_pk_mul_f32 v[44:45], v[44:45], v[214:215]
	v_pk_mul_f32 v[46:47], v[46:47], v[216:217]
	v_pk_mul_f32 v[60:61], v[60:61], v[214:215]
	v_pk_mul_f32 v[62:63], v[62:63], v[216:217]
; #define WAIT_BAR(N) asm volatile("s_waitcnt vmcnt(" #N ") lgkmcnt(0)\n\ts_barrier":::"memory")
;   #define RESC() do{ if(resc){ asm volatile("s_waitcnt lgkmcnt(0)":::"memory"); \
;       _Pragma("unroll") for(int d_=0;d_<2;++d_) _Pragma("unroll") for(int r=0;r<16;++r)o[d_][r]*=wsf[crow(r,hi)]; } }while(0)
;   #define ROT() do{sl_prev=sl_cur;sl_cur=sl_next;sl_next=(sl_next==(NSLOT-1)*SLOTB)?0:sl_next+SLOTB;}while(0)
;   #define ENDW(tt) do{ if((tt)+3<NT){WAIT_BAR(2);} else if((tt)+2<NT){WAIT_BAR(1);} else {WAIT_BAR(0);} }while(0)
; template<int THRL> __device__ __forceinline__ void attn_unit(int b,int qc,int vc,int qb,const bf16*Q,const bf16*__restrict__ K,const bf16*__restrict__ V,bf16*O,char*shm,const int tid){
;     ...
;   for(;t+5<NT;t+=2){
;     STEP(pB0,pB1,pA0,pA1,t,true,true,true);     WAIT_BAR(2); RESC(); ROT();
;     STEP(pA0,pA1,pB0,pB1,t+1,true,true,true);   WAIT_BAR(2); RESC(); ROT();
;   }
;     ...
;   for(;t+1<NT;t+=2){
;     STEP(pB0,pB1,pA0,pA1,t,(t+3<NT),(t+1<NT),(t+1<NT));       ENDW(t);   RESC(); ROT();
;     STEP(pA0,pA1,pB0,pB1,t+1,(t+4<NT),(t+2<NT),(t+2<NT));     ENDW(t+1); RESC(); ROT();
.Lat_noresc_M2:
	s_mov_b32 s21, s16
	s_mov_b32 s16, s17
	s_mov_b32 s17, s18
	s_mov_b32 s18, s21
	s_add_i32 s20, s20, -1
	s_cmp_lg_u32 s20, 0
	s_cbranch_scc1 .Lat_mainloop
.Lat_step_T5:
	v_add_u32_e32 v243, s16, v204
	ds_read_b64_tr_b16 v[214:215], v243 offset:24576
	ds_read_b64_tr_b16 v[216:217], v243 offset:25088
	v_mfma_f32_32x32x16_bf16 v[112:127], v[176:179], v[144:147], v[64:79]
	v_add_f32_e32 v245, v80, v81
	v_add_f32_e32 v245, v82, v245
	v_add_f32_e32 v245, v83, v245
	v_add_f32_e32 v245, v84, v245
	v_add_f32_e32 v245, v85, v245
	v_cvt_pk_bf16_f32 v160, v80, v81
	v_cvt_pk_bf16_f32 v161, v82, v83
	ds_read_b64_tr_b16 v[80:81], v243 offset:28672
	ds_read_b64_tr_b16 v[82:83], v243 offset:29184
	v_mfma_f32_32x32x16_bf16 v[128:143], v[180:183], v[144:147], v[64:79]
	v_add_f32_e32 v245, v86, v245
	v_add_f32_e32 v245, v87, v245
	v_add_f32_e32 v245, v88, v245
	v_add_f32_e32 v245, v89, v245
	v_cvt_pk_bf16_f32 v162, v84, v85
	v_cvt_pk_bf16_f32 v163, v86, v87
	ds_read_b64_tr_b16 v[84:85], v243 offset:25600
	ds_read_b64_tr_b16 v[86:87], v243 offset:26112
	v_mfma_f32_32x32x16_bf16 v[112:127], v[184:187], v[148:151], v[112:127]
	v_add_f32_e32 v245, v90, v245
	v_add_f32_e32 v245, v91, v245
	v_add_f32_e32 v245, v92, v245
	v_add_f32_e32 v245, v93, v245
	v_cvt_pk_bf16_f32 v164, v88, v89
	v_cvt_pk_bf16_f32 v165, v90, v91
	ds_read_b64_tr_b16 v[88:89], v243 offset:29696
	ds_read_b64_tr_b16 v[90:91], v243 offset:30208
	v_mfma_f32_32x32x16_bf16 v[128:143], v[188:191], v[148:151], v[128:143]
	v_add_f32_e32 v245, v94, v245
	v_add_f32_e32 v245, v95, v245
	v_add_f32_e32 v245, v96, v245
	v_add_f32_e32 v245, v97, v245
	v_cvt_pk_bf16_f32 v166, v92, v93
	v_cvt_pk_bf16_f32 v167, v94, v95
	ds_read_b64_tr_b16 v[92:93], v243 offset:26624
	ds_read_b64_tr_b16 v[94:95], v243 offset:27136
	v_mfma_f32_32x32x16_bf16 v[112:127], v[192:195], v[152:155], v[112:127]
	v_add_f32_e32 v245, v98, v245
	v_add_f32_e32 v245, v99, v245
	v_add_f32_e32 v245, v100, v245
	v_add_f32_e32 v245, v101, v245
	v_cvt_pk_bf16_f32 v168, v96, v97
	v_cvt_pk_bf16_f32 v169, v98, v99
	ds_read_b64_tr_b16 v[96:97], v243 offset:30720
	ds_read_b64_tr_b16 v[98:99], v243 offset:31232
	v_mfma_f32_32x32x16_bf16 v[128:143], v[196:199], v[152:155], v[128:143]
	v_add_f32_e32 v245, v102, v245
	v_add_f32_e32 v245, v103, v245
	v_add_f32_e32 v245, v104, v245
	v_add_f32_e32 v245, v105, v245
	v_cvt_pk_bf16_f32 v170, v100, v101
	v_cvt_pk_bf16_f32 v171, v102, v103
	ds_read_b64_tr_b16 v[100:101], v243 offset:27648
	ds_read_b64_tr_b16 v[102:103], v243 offset:28160
	v_mfma_f32_32x32x16_bf16 v[112:127], v[200:203], v[156:159], v[112:127]
	v_add_f32_e32 v245, v106, v245
	v_add_f32_e32 v245, v107, v245
	v_add_f32_e32 v245, v108, v245
	v_add_f32_e32 v245, v109, v245
	v_cvt_pk_bf16_f32 v172, v104, v105
	v_cvt_pk_bf16_f32 v173, v106, v107
	s_waitcnt lgkmcnt(12)
	ds_read_b64_tr_b16 v[104:105], v243 offset:31744
	ds_read_b64_tr_b16 v[106:107], v243 offset:32256
	v_mfma_f32_32x32x16_bf16 v[128:143], v[206:209], v[156:159], v[128:143]
	v_add_f32_e32 v245, v110, v245
	v_add_f32_e32 v245, v111, v245
	v_cvt_pk_bf16_f32 v174, v108, v109
	v_cvt_pk_bf16_f32 v175, v110, v111
	v_add_f32_e32 v211, v211, v245
	s_add_i32 m0, s17, s54
	s_nop 0
	global_load_lds_dwordx4 v222, s[0:1]
	s_add_u32 s0, s0, 0x20000
	s_addc_u32 s1, s1, 0
	s_add_i32 s21, s18, s54
	s_add_i32 m0, s21, 0x6000
	s_nop 0
	global_load_lds_dwordx4 v223, s[4:5]
	s_add_i32 m0, s21, 0xc000
	s_nop 0
	global_load_lds_dwordx4 v224, s[4:5]
	s_add_u32 s4, s4, 0x20000
	s_addc_u32 s5, s5, 0
	v_max3_f32 v246, v112, v113, v114
	v_max3_f32 v247, v115, v116, v117
	v_max3_f32 v246, v246, v118, v119
	v_max3_f32 v247, v247, v120, v121
	v_max3_f32 v246, v246, v122, v123
	v_max3_f32 v247, v247, v124, v125
	v_max3_f32 v246, v246, v126, v127
	v_max3_f32 v247, v247, v128, v129
	v_max3_f32 v246, v246, v130, v131
	v_max3_f32 v247, v247, v132, v133
	v_max3_f32 v246, v246, v134, v135
	v_max3_f32 v247, v247, v136, v137
	v_max3_f32 v246, v246, v138, v139
	v_max3_f32 v247, v247, v140, v141
	v_max3_f32 v246, v246, v142, v143
	v_max_f32_e32 v248, v246, v247
	v_mov_b32_e32 v246, v248
	s_nop 1
	v_permlane32_swap_b32_e32 v248, v246
	v_max_f32_e32 v248, v248, v246
	s_mov_b32 s26, 0
	v_cmp_lt_f32_e32 vcc, s87, v248
	s_cmp_lg_u64 vcc, 0
	s_cbranch_scc1 .Lat_rare_T5

; __device__ __forceinline__ void cmask(f32x16&p0,f32x16&p1,int jb,int qrel,int hi){
;   const float NEG=-INFINITY; int kb=64*jb+4*hi;
;   #pragma unroll
;   for(int r=0;r<16;++r){int kv=kb+(r&3)+8*(r>>2); if(kv>qrel)p0[r]=NEG; if(kv+32>qrel)p1[r]=NEG;}
; }
.Lat_step_T4:
	v_add_u32_e32 v243, s16, v204
	ds_read_b64_tr_b16 v[214:215], v243 offset:24576
	ds_read_b64_tr_b16 v[216:217], v243 offset:25088
	v_mfma_f32_32x32x16_bf16 v[80:95], v[176:179], v[144:147], v[64:79]
	v_add_f32_e32 v245, v112, v113
	v_add_f32_e32 v245, v114, v245
	v_add_f32_e32 v245, v115, v245
	v_add_f32_e32 v245, v116, v245
	v_add_f32_e32 v245, v117, v245
	v_cvt_pk_bf16_f32 v160, v112, v113
	v_cvt_pk_bf16_f32 v161, v114, v115
	ds_read_b64_tr_b16 v[112:113], v243 offset:28672
	ds_read_b64_tr_b16 v[114:115], v243 offset:29184
	v_mfma_f32_32x32x16_bf16 v[96:111], v[180:183], v[144:147], v[64:79]
	v_add_f32_e32 v245, v118, v245
	v_add_f32_e32 v245, v119, v245
	v_add_f32_e32 v245, v120, v245
	v_add_f32_e32 v245, v121, v245
	v_cvt_pk_bf16_f32 v162, v116, v117
	v_cvt_pk_bf16_f32 v163, v118, v119
	ds_read_b64_tr_b16 v[116:117], v243 offset:25600
	ds_read_b64_tr_b16 v[118:119], v243 offset:26112
	v_mfma_f32_32x32x16_bf16 v[80:95], v[184:187], v[148:151], v[80:95]
	v_add_f32_e32 v245, v122, v245
	v_add_f32_e32 v245, v123, v245
	v_add_f32_e32 v245, v124, v245
	v_add_f32_e32 v245, v125, v245
	v_cvt_pk_bf16_f32 v164, v120, v121
	v_cvt_pk_bf16_f32 v165, v122, v123
	ds_read_b64_tr_b16 v[120:121], v243 offset:29696
	ds_read_b64_tr_b16 v[122:123], v243 offset:30208
	v_mfma_f32_32x32x16_bf16 v[96:111], v[188:191], v[148:151], v[96:111]
	v_add_f32_e32 v245, v126, v245
	v_add_f32_e32 v245, v127, v245
	v_add_f32_e32 v245, v128, v245
	v_add_f32_e32 v245, v129, v245
	v_cvt_pk_bf16_f32 v166, v124, v125
	v_cvt_pk_bf16_f32 v167, v126, v127
	ds_read_b64_tr_b16 v[124:125], v243 offset:26624
	ds_read_b64_tr_b16 v[126:127], v243 offset:27136
	v_mfma_f32_32x32x16_bf16 v[80:95], v[192:195], v[152:155], v[80:95]
	v_add_f32_e32 v245, v130, v245
	v_add_f32_e32 v245, v131, v245
	v_add_f32_e32 v245, v132, v245
	v_add_f32_e32 v245, v133, v245
	v_cvt_pk_bf16_f32 v168, v128, v129
	v_cvt_pk_bf16_f32 v169, v130, v131
	ds_read_b64_tr_b16 v[128:129], v243 offset:30720
	ds_read_b64_tr_b16 v[130:131], v243 offset:31232
	v_mfma_f32_32x32x16_bf16 v[96:111], v[196:199], v[152:155], v[96:111]
	v_add_f32_e32 v245, v134, v245
	v_add_f32_e32 v245, v135, v245
	v_add_f32_e32 v245, v136, v245
	v_add_f32_e32 v245, v137, v245
	v_cvt_pk_bf16_f32 v170, v132, v133
	v_cvt_pk_bf16_f32 v171, v134, v135
	ds_read_b64_tr_b16 v[132:133], v243 offset:27648
	ds_read_b64_tr_b16 v[134:135], v243 offset:28160
	v_mfma_f32_32x32x16_bf16 v[80:95], v[200:203], v[156:159], v[80:95]
	v_add_f32_e32 v245, v138, v245
	v_add_f32_e32 v245, v139, v245
	v_add_f32_e32 v245, v140, v245
	v_add_f32_e32 v245, v141, v245
	v_cvt_pk_bf16_f32 v172, v136, v137
	v_cvt_pk_bf16_f32 v173, v138, v139
	s_waitcnt lgkmcnt(12)
	ds_read_b64_tr_b16 v[136:137], v243 offset:31744
	ds_read_b64_tr_b16 v[138:139], v243 offset:32256
	v_mfma_f32_32x32x16_bf16 v[96:111], v[206:209], v[156:159], v[96:111]
	v_add_f32_e32 v245, v142, v245
	v_add_f32_e32 v245, v143, v245
	v_cvt_pk_bf16_f32 v174, v140, v141
	v_cvt_pk_bf16_f32 v175, v142, v143
	v_add_f32_e32 v211, v211, v245
	s_add_i32 m0, s17, s54
	s_nop 0
	global_load_lds_dwordx4 v222, s[0:1]
	s_add_u32 s0, s0, 0x20000
	s_addc_u32 s1, s1, 0
	s_add_i32 s21, s18, s54
	s_add_i32 m0, s21, 0x6000
	s_nop 0
	global_load_lds_dwordx4 v223, s[4:5]
	s_add_i32 m0, s21, 0xc000
	s_nop 0
	global_load_lds_dwordx4 v224, s[4:5]
	s_add_u32 s4, s4, 0x20000
	s_addc_u32 s5, s5, 0
	v_cmp_gt_i32_e64 s[28:29], 0, v225
	v_cmp_gt_i32_e64 s[30:31], 32, v225
	v_cmp_gt_i32_e64 s[34:35], 1, v225
	v_cndmask_b32_e64 v80, v80, v241, s[28:29]
	v_cmp_gt_i32_e64 s[28:29], 33, v225
	v_cndmask_b32_e64 v96, v96, v241, s[30:31]
	v_cmp_gt_i32_e64 s[30:31], 2, v225
	v_cndmask_b32_e64 v81, v81, v241, s[34:35]
	v_cmp_gt_i32_e64 s[34:35], 34, v225
	v_cndmask_b32_e64 v97, v97, v241, s[28:29]
	v_cmp_gt_i32_e64 s[28:29], 3, v225
	v_cndmask_b32_e64 v82, v82, v241, s[30:31]
	v_cmp_gt_i32_e64 s[30:31], 35, v225
	v_cndmask_b32_e64 v98, v98, v241, s[34:35]
	v_cmp_gt_i32_e64 s[34:35], 8, v225
	v_cndmask_b32_e64 v83, v83, v241, s[28:29]
	v_cmp_gt_i32_e64 s[28:29], 40, v225
	v_cndmask_b32_e64 v99, v99, v241, s[30:31]
	v_cmp_gt_i32_e64 s[30:31], 9, v225
	v_cndmask_b32_e64 v84, v84, v241, s[34:35]
	v_cmp_gt_i32_e64 s[34:35], 41, v225
	v_cndmask_b32_e64 v100, v100, v241, s[28:29]
	v_cmp_gt_i32_e64 s[28:29], 10, v225
	v_cndmask_b32_e64 v85, v85, v241, s[30:31]
	v_cmp_gt_i32_e64 s[30:31], 42, v225
	v_cndmask_b32_e64 v101, v101, v241, s[34:35]
	v_cmp_gt_i32_e64 s[34:35], 11, v225
	v_cndmask_b32_e64 v86, v86, v241, s[28:29]
	v_cmp_gt_i32_e64 s[28:29], 43, v225
	v_cndmask_b32_e64 v102, v102, v241, s[30:31]
	v_cmp_gt_i32_e64 s[30:31], 16, v225
	v_cndmask_b32_e64 v87, v87, v241, s[34:35]
	v_cmp_gt_i32_e64 s[34:35], 48, v225
	v_cndmask_b32_e64 v103, v103, v241, s[28:29]
	v_cmp_gt_i32_e64 s[28:29], 17, v225
	v_cndmask_b32_e64 v88, v88, v241, s[30:31]
	v_cmp_gt_i32_e64 s[30:31], 49, v225
	v_cndmask_b32_e64 v104, v104, v241, s[34:35]
	v_cmp_gt_i32_e64 s[34:35], 18, v225
	v_cndmask_b32_e64 v89, v89, v241, s[28:29]
	v_cmp_gt_i32_e64 s[28:29], 50, v225
	v_cndmask_b32_e64 v105, v105, v241, s[30:31]
	v_cmp_gt_i32_e64 s[30:31], 19, v225
	v_cndmask_b32_e64 v90, v90, v241, s[34:35]
	v_cmp_gt_i32_e64 s[34:35], 51, v225
	v_cndmask_b32_e64 v106, v106, v241, s[28:29]
	v_cmp_gt_i32_e64 s[28:29], 24, v225
	v_cndmask_b32_e64 v91, v91, v241, s[30:31]
	v_cmp_gt_i32_e64 s[30:31], 56, v225
	v_cndmask_b32_e64 v107, v107, v241, s[34:35]
	v_cmp_gt_i32_e64 s[34:35], 25, v225
	v_cndmask_b32_e64 v92, v92, v241, s[28:29]
	v_cmp_gt_i32_e64 s[28:29], 57, v225
	v_cndmask_b32_e64 v108, v108, v241, s[30:31]
	v_cmp_gt_i32_e64 s[30:31], 26, v225
	v_cndmask_b32_e64 v93, v93, v241, s[34:35]
	v_cmp_gt_i32_e64 s[34:35], 58, v225
	v_cndmask_b32_e64 v109, v109, v241, s[28:29]
	v_cmp_gt_i32_e64 s[28:29], 27, v225
	v_cndmask_b32_e64 v94, v94, v241, s[30:31]
	v_cmp_gt_i32_e64 s[30:31], 59, v225
	v_cndmask_b32_e64 v110, v110, v241, s[34:35]
	v_cndmask_b32_e64 v95, v95, v241, s[28:29]
	v_cndmask_b32_e64 v111, v111, v241, s[30:31]
	v_max3_f32 v246, v80, v81, v82
	v_max3_f32 v247, v83, v84, v85
	v_max3_f32 v246, v246, v86, v87
	v_max3_f32 v247, v247, v88, v89
	v_max3_f32 v246, v246, v90, v91
	v_max3_f32 v247, v247, v92, v93
	v_max3_f32 v246, v246, v94, v95
	v_max3_f32 v247, v247, v96, v97
	v_max3_f32 v246, v246, v98, v99
	v_max3_f32 v247, v247, v100, v101
	v_max3_f32 v246, v246, v102, v103
	v_max3_f32 v247, v247, v104, v105
	v_max3_f32 v246, v246, v106, v107
	v_max3_f32 v247, v247, v108, v109
	v_max3_f32 v246, v246, v110, v111
	v_max_f32_e32 v248, v246, v247
	v_mov_b32_e32 v246, v248
	s_nop 1
	v_permlane32_swap_b32_e32 v248, v246
	v_max_f32_e32 v248, v248, v246
	s_mov_b32 s26, 0
	v_cmp_lt_f32_e32 vcc, s87, v248
	s_cmp_lg_u64 vcc, 0
	s_cbranch_scc1 .Lat_rare_T4

; __device__ __forceinline__ void cmask(f32x16&p0,f32x16&p1,int jb,int qrel,int hi){
;   const float NEG=-INFINITY; int kb=64*jb+4*hi;
;   #pragma unroll
;   for(int r=0;r<16;++r){int kv=kb+(r&3)+8*(r>>2); if(kv>qrel)p0[r]=NEG; if(kv+32>qrel)p1[r]=NEG;}
; }
.Lat_step_T3:
	v_add_u32_e32 v243, s16, v204
	ds_read_b64_tr_b16 v[214:215], v243 offset:24576
	ds_read_b64_tr_b16 v[216:217], v243 offset:25088
	v_mfma_f32_32x32x16_bf16 v[112:127], v[176:179], v[144:147], v[64:79]
	v_add_f32_e32 v245, v80, v81
	v_add_f32_e32 v245, v82, v245
	v_add_f32_e32 v245, v83, v245
	v_add_f32_e32 v245, v84, v245
	v_add_f32_e32 v245, v85, v245
	v_cvt_pk_bf16_f32 v160, v80, v81
	v_cvt_pk_bf16_f32 v161, v82, v83
	ds_read_b64_tr_b16 v[80:81], v243 offset:28672
	ds_read_b64_tr_b16 v[82:83], v243 offset:29184
	v_mfma_f32_32x32x16_bf16 v[128:143], v[180:183], v[144:147], v[64:79]
	v_add_f32_e32 v245, v86, v245
	v_add_f32_e32 v245, v87, v245
	v_add_f32_e32 v245, v88, v245
	v_add_f32_e32 v245, v89, v245
	v_cvt_pk_bf16_f32 v162, v84, v85
	v_cvt_pk_bf16_f32 v163, v86, v87
	ds_read_b64_tr_b16 v[84:85], v243 offset:25600
	ds_read_b64_tr_b16 v[86:87], v243 offset:26112
	v_mfma_f32_32x32x16_bf16 v[112:127], v[184:187], v[148:151], v[112:127]
	v_add_f32_e32 v245, v90, v245
	v_add_f32_e32 v245, v91, v245
	v_add_f32_e32 v245, v92, v245
	v_add_f32_e32 v245, v93, v245
	v_cvt_pk_bf16_f32 v164, v88, v89
	v_cvt_pk_bf16_f32 v165, v90, v91
	ds_read_b64_tr_b16 v[88:89], v243 offset:29696
	ds_read_b64_tr_b16 v[90:91], v243 offset:30208
	v_mfma_f32_32x32x16_bf16 v[128:143], v[188:191], v[148:151], v[128:143]
	v_add_f32_e32 v245, v94, v245
	v_add_f32_e32 v245, v95, v245
	v_add_f32_e32 v245, v96, v245
	v_add_f32_e32 v245, v97, v245
	v_cvt_pk_bf16_f32 v166, v92, v93
	v_cvt_pk_bf16_f32 v167, v94, v95
	ds_read_b64_tr_b16 v[92:93], v243 offset:26624
	ds_read_b64_tr_b16 v[94:95], v243 offset:27136
	v_mfma_f32_32x32x16_bf16 v[112:127], v[192:195], v[152:155], v[112:127]
	v_add_f32_e32 v245, v98, v245
	v_add_f32_e32 v245, v99, v245
	v_add_f32_e32 v245, v100, v245
	v_add_f32_e32 v245, v101, v245
	v_cvt_pk_bf16_f32 v168, v96, v97
	v_cvt_pk_bf16_f32 v169, v98, v99
	ds_read_b64_tr_b16 v[96:97], v243 offset:30720
	ds_read_b64_tr_b16 v[98:99], v243 offset:31232
	v_mfma_f32_32x32x16_bf16 v[128:143], v[196:199], v[152:155], v[128:143]
	v_add_f32_e32 v245, v102, v245
	v_add_f32_e32 v245, v103, v245
	v_add_f32_e32 v245, v104, v245
	v_add_f32_e32 v245, v105, v245
	v_cvt_pk_bf16_f32 v170, v100, v101
	v_cvt_pk_bf16_f32 v171, v102, v103
	ds_read_b64_tr_b16 v[100:101], v243 offset:27648
	ds_read_b64_tr_b16 v[102:103], v243 offset:28160
	v_mfma_f32_32x32x16_bf16 v[112:127], v[200:203], v[156:159], v[112:127]
	v_add_f32_e32 v245, v106, v245
	v_add_f32_e32 v245, v107, v245
	v_add_f32_e32 v245, v108, v245
	v_add_f32_e32 v245, v109, v245
	v_cvt_pk_bf16_f32 v172, v104, v105
	v_cvt_pk_bf16_f32 v173, v106, v107
	s_waitcnt lgkmcnt(12)
	ds_read_b64_tr_b16 v[104:105], v243 offset:31744
	ds_read_b64_tr_b16 v[106:107], v243 offset:32256
	v_mfma_f32_32x32x16_bf16 v[128:143], v[206:209], v[156:159], v[128:143]
	v_add_f32_e32 v245, v110, v245
	v_add_f32_e32 v245, v111, v245
	v_cvt_pk_bf16_f32 v174, v108, v109
	v_cvt_pk_bf16_f32 v175, v110, v111
	v_add_f32_e32 v211, v211, v245
	s_add_i32 s21, s18, s54
	s_add_i32 m0, s21, 0x6000
	s_nop 0
	global_load_lds_dwordx4 v223, s[4:5]
	s_add_i32 m0, s21, 0xc000
	s_nop 0
	global_load_lds_dwordx4 v224, s[4:5]
	s_add_u32 s4, s4, 0x20000
	s_addc_u32 s5, s5, 0
	v_add_u32_e32 v242, 0xffffffc0, v225
	v_cmp_gt_i32_e64 s[28:29], 0, v242
	v_cmp_gt_i32_e64 s[30:31], 32, v242
	v_cmp_gt_i32_e64 s[34:35], 1, v242
	v_cndmask_b32_e64 v112, v112, v241, s[28:29]
	v_cmp_gt_i32_e64 s[28:29], 33, v242
	v_cndmask_b32_e64 v128, v128, v241, s[30:31]
	v_cmp_gt_i32_e64 s[30:31], 2, v242
	v_cndmask_b32_e64 v113, v113, v241, s[34:35]
	v_cmp_gt_i32_e64 s[34:35], 34, v242
	v_cndmask_b32_e64 v129, v129, v241, s[28:29]
	v_cmp_gt_i32_e64 s[28:29], 3, v242
	v_cndmask_b32_e64 v114, v114, v241, s[30:31]
	v_cmp_gt_i32_e64 s[30:31], 35, v242
	v_cndmask_b32_e64 v130, v130, v241, s[34:35]
	v_cmp_gt_i32_e64 s[34:35], 8, v242
	v_cndmask_b32_e64 v115, v115, v241, s[28:29]
	v_cmp_gt_i32_e64 s[28:29], 40, v242
	v_cndmask_b32_e64 v131, v131, v241, s[30:31]
	v_cmp_gt_i32_e64 s[30:31], 9, v242
	v_cndmask_b32_e64 v116, v116, v241, s[34:35]
	v_cmp_gt_i32_e64 s[34:35], 41, v242
	v_cndmask_b32_e64 v132, v132, v241, s[28:29]
	v_cmp_gt_i32_e64 s[28:29], 10, v242
	v_cndmask_b32_e64 v117, v117, v241, s[30:31]
	v_cmp_gt_i32_e64 s[30:31], 42, v242
	v_cndmask_b32_e64 v133, v133, v241, s[34:35]
	v_cmp_gt_i32_e64 s[34:35], 11, v242
	v_cndmask_b32_e64 v118, v118, v241, s[28:29]
	v_cmp_gt_i32_e64 s[28:29], 43, v242
	v_cndmask_b32_e64 v134, v134, v241, s[30:31]
	v_cmp_gt_i32_e64 s[30:31], 16, v242
	v_cndmask_b32_e64 v119, v119, v241, s[34:35]
	v_cmp_gt_i32_e64 s[34:35], 48, v242
	v_cndmask_b32_e64 v135, v135, v241, s[28:29]
	v_cmp_gt_i32_e64 s[28:29], 17, v242
	v_cndmask_b32_e64 v120, v120, v241, s[30:31]
	v_cmp_gt_i32_e64 s[30:31], 49, v242
	v_cndmask_b32_e64 v136, v136, v241, s[34:35]
	v_cmp_gt_i32_e64 s[34:35], 18, v242
	v_cndmask_b32_e64 v121, v121, v241, s[28:29]
	v_cmp_gt_i32_e64 s[28:29], 50, v242
	v_cndmask_b32_e64 v137, v137, v241, s[30:31]
	v_cmp_gt_i32_e64 s[30:31], 19, v242
	v_cndmask_b32_e64 v122, v122, v241, s[34:35]
	v_cmp_gt_i32_e64 s[34:35], 51, v242
	v_cndmask_b32_e64 v138, v138, v241, s[28:29]
	v_cmp_gt_i32_e64 s[28:29], 24, v242
	v_cndmask_b32_e64 v123, v123, v241, s[30:31]
	v_cmp_gt_i32_e64 s[30:31], 56, v242
	v_cndmask_b32_e64 v139, v139, v241, s[34:35]
	v_cmp_gt_i32_e64 s[34:35], 25, v242
	v_cndmask_b32_e64 v124, v124, v241, s[28:29]
	v_cmp_gt_i32_e64 s[28:29], 57, v242
	v_cndmask_b32_e64 v140, v140, v241, s[30:31]
	v_cmp_gt_i32_e64 s[30:31], 26, v242
	v_cndmask_b32_e64 v125, v125, v241, s[34:35]
	v_cmp_gt_i32_e64 s[34:35], 58, v242
	v_cndmask_b32_e64 v141, v141, v241, s[28:29]
	v_cmp_gt_i32_e64 s[28:29], 27, v242
	v_cndmask_b32_e64 v126, v126, v241, s[30:31]
	v_cmp_gt_i32_e64 s[30:31], 59, v242
	v_cndmask_b32_e64 v142, v142, v241, s[34:35]
	v_cndmask_b32_e64 v127, v127, v241, s[28:29]
	v_cndmask_b32_e64 v143, v143, v241, s[30:31]
	v_max3_f32 v246, v112, v113, v114
	v_max3_f32 v247, v115, v116, v117
	v_max3_f32 v246, v246, v118, v119
	v_max3_f32 v247, v247, v120, v121
	v_max3_f32 v246, v246, v122, v123
	v_max3_f32 v247, v247, v124, v125
	v_max3_f32 v246, v246, v126, v127
	v_max3_f32 v247, v247, v128, v129
	v_max3_f32 v246, v246, v130, v131
	v_max3_f32 v247, v247, v132, v133
	v_max3_f32 v246, v246, v134, v135
	v_max3_f32 v247, v247, v136, v137
	v_max3_f32 v246, v246, v138, v139
	v_max3_f32 v247, v247, v140, v141
	v_max3_f32 v246, v246, v142, v143
	v_max_f32_e32 v248, v246, v247
	v_mov_b32_e32 v246, v248
	s_nop 1
	v_permlane32_swap_b32_e32 v248, v246
	v_max_f32_e32 v248, v248, v246
	s_mov_b32 s26, 0
	v_cmp_lt_f32_e32 vcc, s87, v248
	s_cmp_lg_u64 vcc, 0
	s_cbranch_scc1 .Lat_rare_T3
;   #define RESC() do{ if(resc){ asm volatile("s_waitcnt lgkmcnt(0)":::"memory"); \
;       _Pragma("unroll") for(int d_=0;d_<2;++d_) _Pragma("unroll") for(int r=0;r<16;++r)o[d_][r]*=wsf[crow(r,hi)]; } }while(0)
;   #define ROT() do{sl_prev=sl_cur;sl_cur=sl_next;sl_next=(sl_next==(NSLOT-1)*SLOTB)?0:sl_next+SLOTB;}while(0)
;   #define ENDW(tt) do{ if((tt)+3<NT){WAIT_BAR(2);} else if((tt)+2<NT){WAIT_BAR(1);} else {WAIT_BAR(0);} }while(0)
; template<int THRL> __device__ __forceinline__ void attn_unit(int b,int qc,int vc,int qb,const bf16*Q,const bf16*__restrict__ K,const bf16*__restrict__ V,bf16*O,char*shm,const int tid){
;     ...
;   for(;t+1<NT;t+=2){
;     STEP(pB0,pB1,pA0,pA1,t,(t+3<NT),(t+1<NT),(t+1<NT));       ENDW(t);   RESC(); ROT();
;     STEP(pA0,pA1,pB0,pB1,t+1,(t+4<NT),(t+2<NT),(t+2<NT));     ENDW(t+1); RESC(); ROT();
.Lat_cont_T3:
	v_add_u32_e32 v244, s18, v219
	v_mfma_f32_32x32x16_bf16 v[0:15], v[160:163], v[214:217], v[0:15]
	v_exp_f32_e32 v112, v112
	v_exp_f32_e32 v113, v113
	s_waitcnt lgkmcnt(12)
	ds_read_b64_tr_b16 v[214:215], v243 offset:49152
	ds_read_b64_tr_b16 v[216:217], v243 offset:49664
	v_mfma_f32_32x32x16_bf16 v[16:31], v[160:163], v[80:83], v[16:31]
	v_exp_f32_e32 v114, v114
	v_exp_f32_e32 v115, v115
	s_waitcnt lgkmcnt(12)
	ds_read_b64_tr_b16 v[80:81], v243 offset:53248
	ds_read_b64_tr_b16 v[82:83], v243 offset:53760
	v_mfma_f32_32x32x16_bf16 v[0:15], v[164:167], v[84:87], v[0:15]
	v_exp_f32_e32 v116, v116
	v_exp_f32_e32 v117, v117
	s_waitcnt lgkmcnt(12)
	ds_read_b64_tr_b16 v[84:85], v243 offset:50176
	ds_read_b64_tr_b16 v[86:87], v243 offset:50688
	v_mfma_f32_32x32x16_bf16 v[16:31], v[164:167], v[88:91], v[16:31]
	v_exp_f32_e32 v118, v118
	v_exp_f32_e32 v119, v119
	s_waitcnt lgkmcnt(12)
	ds_read_b64_tr_b16 v[88:89], v243 offset:54272
	ds_read_b64_tr_b16 v[90:91], v243 offset:54784
	v_mfma_f32_32x32x16_bf16 v[0:15], v[168:171], v[92:95], v[0:15]
	v_exp_f32_e32 v120, v120
	v_exp_f32_e32 v121, v121
	s_waitcnt lgkmcnt(12)
	ds_read_b64_tr_b16 v[92:93], v243 offset:51200
	ds_read_b64_tr_b16 v[94:95], v243 offset:51712
	v_mfma_f32_32x32x16_bf16 v[16:31], v[168:171], v[96:99], v[16:31]
	v_exp_f32_e32 v122, v122
	v_exp_f32_e32 v123, v123
	s_waitcnt lgkmcnt(12)
	ds_read_b64_tr_b16 v[96:97], v243 offset:55296
	ds_read_b64_tr_b16 v[98:99], v243 offset:55808
	v_mfma_f32_32x32x16_bf16 v[0:15], v[172:175], v[100:103], v[0:15]
	v_exp_f32_e32 v124, v124
	v_exp_f32_e32 v125, v125
	s_waitcnt lgkmcnt(12)
	ds_read_b64_tr_b16 v[100:101], v243 offset:52224
	ds_read_b64_tr_b16 v[102:103], v243 offset:52736
	v_mfma_f32_32x32x16_bf16 v[16:31], v[172:175], v[104:107], v[16:31]
	v_exp_f32_e32 v126, v126
	v_exp_f32_e32 v127, v127
	s_waitcnt lgkmcnt(12)
	ds_read_b64_tr_b16 v[104:105], v243 offset:56320
	ds_read_b64_tr_b16 v[106:107], v243 offset:56832
	v_mfma_f32_32x32x16_bf16 v[32:47], v[160:163], v[214:217], v[32:47]
	v_exp_f32_e32 v128, v128
	v_exp_f32_e32 v129, v129
	s_waitcnt lgkmcnt(12)
	ds_read_b128 v[176:179], v244 offset:0
	ds_read_b128 v[180:183], v244 offset:512
	v_mfma_f32_32x32x16_bf16 v[48:63], v[160:163], v[80:83], v[48:63]
	v_exp_f32_e32 v130, v130
	v_exp_f32_e32 v131, v131
	s_waitcnt lgkmcnt(12)
	ds_read_b128 v[184:187], v244 offset:2048
	ds_read_b128 v[188:191], v244 offset:2560
	v_mfma_f32_32x32x16_bf16 v[32:47], v[164:167], v[84:87], v[32:47]
	v_exp_f32_e32 v132, v132
	v_exp_f32_e32 v133, v133
	s_waitcnt lgkmcnt(12)
	ds_read_b128 v[192:195], v244 offset:4096
	ds_read_b128 v[196:199], v244 offset:4608
	v_mfma_f32_32x32x16_bf16 v[48:63], v[164:167], v[88:91], v[48:63]
	v_exp_f32_e32 v134, v134
	v_exp_f32_e32 v135, v135
	s_waitcnt lgkmcnt(12)
	ds_read_b128 v[200:203], v244 offset:6144
	ds_read_b128 v[206:209], v244 offset:6656
	v_mfma_f32_32x32x16_bf16 v[32:47], v[168:171], v[92:95], v[32:47]
	v_exp_f32_e32 v136, v136
	v_exp_f32_e32 v137, v137
	s_waitcnt lgkmcnt(12)
	v_mfma_f32_32x32x16_bf16 v[48:63], v[168:171], v[96:99], v[48:63]
	v_exp_f32_e32 v138, v138
	v_exp_f32_e32 v139, v139
	s_waitcnt lgkmcnt(10)
	v_mfma_f32_32x32x16_bf16 v[32:47], v[172:175], v[100:103], v[32:47]
	v_exp_f32_e32 v140, v140
	v_exp_f32_e32 v141, v141
	s_waitcnt lgkmcnt(8)
	v_mfma_f32_32x32x16_bf16 v[48:63], v[172:175], v[104:107], v[48:63]
	v_exp_f32_e32 v142, v142
	v_exp_f32_e32 v143, v143
	s_waitcnt vmcnt(2) lgkmcnt(0)
	s_barrier
	s_cmp_eq_u32 s26, 0
	s_cbranch_scc1 .Lat_noresc_T3
	s_waitcnt lgkmcnt(0)
	ds_read_b128 v[214:217], v227 offset:0
	s_waitcnt lgkmcnt(0)
	v_pk_mul_f32 v[0:1], v[0:1], v[214:215]
	v_pk_mul_f32 v[2:3], v[2:3], v[216:217]
	v_pk_mul_f32 v[16:17], v[16:17], v[214:215]
	v_pk_mul_f32 v[18:19], v[18:19], v[216:217]
	v_pk_mul_f32 v[32:33], v[32:33], v[214:215]
	v_pk_mul_f32 v[34:35], v[34:35], v[216:217]
	v_pk_mul_f32 v[48:49], v[48:49], v[214:215]
	v_pk_mul_f32 v[50:51], v[50:51], v[216:217]
	ds_read_b128 v[214:217], v227 offset:32
	s_waitcnt lgkmcnt(0)
	v_pk_mul_f32 v[4:5], v[4:5], v[214:215]
	v_pk_mul_f32 v[6:7], v[6:7], v[216:217]
	v_pk_mul_f32 v[20:21], v[20:21], v[214:215]
	v_pk_mul_f32 v[22:23], v[22:23], v[216:217]
	v_pk_mul_f32 v[36:37], v[36:37], v[214:215]
	v_pk_mul_f32 v[38:39], v[38:39], v[216:217]
	v_pk_mul_f32 v[52:53], v[52:53], v[214:215]
	v_pk_mul_f32 v[54:55], v[54:55], v[216:217]
	ds_read_b128 v[214:217], v227 offset:64
	s_waitcnt lgkmcnt(0)
	v_pk_mul_f32 v[8:9], v[8:9], v[214:215]
	v_pk_mul_f32 v[10:11], v[10:11], v[216:217]
	v_pk_mul_f32 v[24:25], v[24:25], v[214:215]
	v_pk_mul_f32 v[26:27], v[26:27], v[216:217]
	v_pk_mul_f32 v[40:41], v[40:41], v[214:215]
	v_pk_mul_f32 v[42:43], v[42:43], v[216:217]
	v_pk_mul_f32 v[56:57], v[56:57], v[214:215]
	v_pk_mul_f32 v[58:59], v[58:59], v[216:217]
	ds_read_b128 v[214:217], v227 offset:96
	s_waitcnt lgkmcnt(0)
	v_pk_mul_f32 v[12:13], v[12:13], v[214:215]
	v_pk_mul_f32 v[14:15], v[14:15], v[216:217]
	v_pk_mul_f32 v[28:29], v[28:29], v[214:215]
	v_pk_mul_f32 v[30:31], v[30:31], v[216:217]
	v_pk_mul_f32 v[44:45], v[44:45], v[214:215]
	v_pk_mul_f32 v[46:47], v[46:47], v[216:217]
	v_pk_mul_f32 v[60:61], v[60:61], v[214:215]
	v_pk_mul_f32 v[62:63], v[62:63], v[216:217]

; __device__ __forceinline__ void cmask(f32x16&p0,f32x16&p1,int jb,int qrel,int hi){
;   const float NEG=-INFINITY; int kb=64*jb+4*hi;
;   #pragma unroll
;   for(int r=0;r<16;++r){int kv=kb+(r&3)+8*(r>>2); if(kv>qrel)p0[r]=NEG; if(kv+32>qrel)p1[r]=NEG;}
; }
.Lat_step_T2:
	v_add_u32_e32 v243, s16, v204
	ds_read_b64_tr_b16 v[214:215], v243 offset:24576
	ds_read_b64_tr_b16 v[216:217], v243 offset:25088
	v_mfma_f32_32x32x16_bf16 v[80:95], v[176:179], v[144:147], v[64:79]
	v_add_f32_e32 v245, v112, v113
	v_add_f32_e32 v245, v114, v245
	v_add_f32_e32 v245, v115, v245
	v_add_f32_e32 v245, v116, v245
	v_add_f32_e32 v245, v117, v245
	v_cvt_pk_bf16_f32 v160, v112, v113
	v_cvt_pk_bf16_f32 v161, v114, v115
	ds_read_b64_tr_b16 v[112:113], v243 offset:28672
	ds_read_b64_tr_b16 v[114:115], v243 offset:29184
	v_mfma_f32_32x32x16_bf16 v[96:111], v[180:183], v[144:147], v[64:79]
	v_add_f32_e32 v245, v118, v245
	v_add_f32_e32 v245, v119, v245
	v_add_f32_e32 v245, v120, v245
	v_add_f32_e32 v245, v121, v245
	v_cvt_pk_bf16_f32 v162, v116, v117
	v_cvt_pk_bf16_f32 v163, v118, v119
	ds_read_b64_tr_b16 v[116:117], v243 offset:25600
	ds_read_b64_tr_b16 v[118:119], v243 offset:26112
	v_mfma_f32_32x32x16_bf16 v[80:95], v[184:187], v[148:151], v[80:95]
	v_add_f32_e32 v245, v122, v245
	v_add_f32_e32 v245, v123, v245
	v_add_f32_e32 v245, v124, v245
	v_add_f32_e32 v245, v125, v245
	v_cvt_pk_bf16_f32 v164, v120, v121
	v_cvt_pk_bf16_f32 v165, v122, v123
	ds_read_b64_tr_b16 v[120:121], v243 offset:29696
	ds_read_b64_tr_b16 v[122:123], v243 offset:30208
	v_mfma_f32_32x32x16_bf16 v[96:111], v[188:191], v[148:151], v[96:111]
	v_add_f32_e32 v245, v126, v245
	v_add_f32_e32 v245, v127, v245
	v_add_f32_e32 v245, v128, v245
	v_add_f32_e32 v245, v129, v245
	v_cvt_pk_bf16_f32 v166, v124, v125
	v_cvt_pk_bf16_f32 v167, v126, v127
	ds_read_b64_tr_b16 v[124:125], v243 offset:26624
	ds_read_b64_tr_b16 v[126:127], v243 offset:27136
	v_mfma_f32_32x32x16_bf16 v[80:95], v[192:195], v[152:155], v[80:95]
	v_add_f32_e32 v245, v130, v245
	v_add_f32_e32 v245, v131, v245
	v_add_f32_e32 v245, v132, v245
	v_add_f32_e32 v245, v133, v245
	v_cvt_pk_bf16_f32 v168, v128, v129
	v_cvt_pk_bf16_f32 v169, v130, v131
	ds_read_b64_tr_b16 v[128:129], v243 offset:30720
	ds_read_b64_tr_b16 v[130:131], v243 offset:31232
	v_mfma_f32_32x32x16_bf16 v[96:111], v[196:199], v[152:155], v[96:111]
	v_add_f32_e32 v245, v134, v245
	v_add_f32_e32 v245, v135, v245
	v_add_f32_e32 v245, v136, v245
	v_add_f32_e32 v245, v137, v245
	v_cvt_pk_bf16_f32 v170, v132, v133
	v_cvt_pk_bf16_f32 v171, v134, v135
	ds_read_b64_tr_b16 v[132:133], v243 offset:27648
	ds_read_b64_tr_b16 v[134:135], v243 offset:28160
	v_mfma_f32_32x32x16_bf16 v[80:95], v[200:203], v[156:159], v[80:95]
	v_add_f32_e32 v245, v138, v245
	v_add_f32_e32 v245, v139, v245
	v_add_f32_e32 v245, v140, v245
	v_add_f32_e32 v245, v141, v245
	v_cvt_pk_bf16_f32 v172, v136, v137
	v_cvt_pk_bf16_f32 v173, v138, v139
	s_waitcnt lgkmcnt(12)
	ds_read_b64_tr_b16 v[136:137], v243 offset:31744
	ds_read_b64_tr_b16 v[138:139], v243 offset:32256
	v_mfma_f32_32x32x16_bf16 v[96:111], v[206:209], v[156:159], v[96:111]
	v_add_f32_e32 v245, v142, v245
	v_add_f32_e32 v245, v143, v245
	v_cvt_pk_bf16_f32 v174, v140, v141
	v_cvt_pk_bf16_f32 v175, v142, v143
	v_add_f32_e32 v211, v211, v245
	s_add_i32 s21, s18, s54
	s_add_i32 m0, s21, 0x6000
	s_nop 0
	global_load_lds_dwordx4 v223, s[4:5]
	s_add_i32 m0, s21, 0xc000
	s_nop 0
	global_load_lds_dwordx4 v224, s[4:5]
	s_add_u32 s4, s4, 0x20000
	s_addc_u32 s5, s5, 0
	v_add_u32_e32 v242, 0xffffff80, v225
	v_cmp_gt_i32_e64 s[28:29], 0, v242
	v_cmp_gt_i32_e64 s[30:31], 32, v242
	v_cmp_gt_i32_e64 s[34:35], 1, v242
	v_cndmask_b32_e64 v80, v80, v241, s[28:29]
	v_cmp_gt_i32_e64 s[28:29], 33, v242
	v_cndmask_b32_e64 v96, v96, v241, s[30:31]
	v_cmp_gt_i32_e64 s[30:31], 2, v242
	v_cndmask_b32_e64 v81, v81, v241, s[34:35]
	v_cmp_gt_i32_e64 s[34:35], 34, v242
	v_cndmask_b32_e64 v97, v97, v241, s[28:29]
	v_cmp_gt_i32_e64 s[28:29], 3, v242
	v_cndmask_b32_e64 v82, v82, v241, s[30:31]
	v_cmp_gt_i32_e64 s[30:31], 35, v242
	v_cndmask_b32_e64 v98, v98, v241, s[34:35]
	v_cmp_gt_i32_e64 s[34:35], 8, v242
	v_cndmask_b32_e64 v83, v83, v241, s[28:29]
	v_cmp_gt_i32_e64 s[28:29], 40, v242
	v_cndmask_b32_e64 v99, v99, v241, s[30:31]
	v_cmp_gt_i32_e64 s[30:31], 9, v242
	v_cndmask_b32_e64 v84, v84, v241, s[34:35]
	v_cmp_gt_i32_e64 s[34:35], 41, v242
	v_cndmask_b32_e64 v100, v100, v241, s[28:29]
	v_cmp_gt_i32_e64 s[28:29], 10, v242
	v_cndmask_b32_e64 v85, v85, v241, s[30:31]
	v_cmp_gt_i32_e64 s[30:31], 42, v242
	v_cndmask_b32_e64 v101, v101, v241, s[34:35]
	v_cmp_gt_i32_e64 s[34:35], 11, v242
	v_cndmask_b32_e64 v86, v86, v241, s[28:29]
	v_cmp_gt_i32_e64 s[28:29], 43, v242
	v_cndmask_b32_e64 v102, v102, v241, s[30:31]
	v_cmp_gt_i32_e64 s[30:31], 16, v242
	v_cndmask_b32_e64 v87, v87, v241, s[34:35]
	v_cmp_gt_i32_e64 s[34:35], 48, v242
	v_cndmask_b32_e64 v103, v103, v241, s[28:29]
	v_cmp_gt_i32_e64 s[28:29], 17, v242
	v_cndmask_b32_e64 v88, v88, v241, s[30:31]
	v_cmp_gt_i32_e64 s[30:31], 49, v242
	v_cndmask_b32_e64 v104, v104, v241, s[34:35]
	v_cmp_gt_i32_e64 s[34:35], 18, v242
	v_cndmask_b32_e64 v89, v89, v241, s[28:29]
	v_cmp_gt_i32_e64 s[28:29], 50, v242
	v_cndmask_b32_e64 v105, v105, v241, s[30:31]
	v_cmp_gt_i32_e64 s[30:31], 19, v242
	v_cndmask_b32_e64 v90, v90, v241, s[34:35]
	v_cmp_gt_i32_e64 s[34:35], 51, v242
	v_cndmask_b32_e64 v106, v106, v241, s[28:29]
	v_cmp_gt_i32_e64 s[28:29], 24, v242
	v_cndmask_b32_e64 v91, v91, v241, s[30:31]
	v_cmp_gt_i32_e64 s[30:31], 56, v242
	v_cndmask_b32_e64 v107, v107, v241, s[34:35]
	v_cmp_gt_i32_e64 s[34:35], 25, v242
	v_cndmask_b32_e64 v92, v92, v241, s[28:29]
	v_cmp_gt_i32_e64 s[28:29], 57, v242
	v_cndmask_b32_e64 v108, v108, v241, s[30:31]
	v_cmp_gt_i32_e64 s[30:31], 26, v242
	v_cndmask_b32_e64 v93, v93, v241, s[34:35]
	v_cmp_gt_i32_e64 s[34:35], 58, v242
	v_cndmask_b32_e64 v109, v109, v241, s[28:29]
	v_cmp_gt_i32_e64 s[28:29], 27, v242
	v_cndmask_b32_e64 v94, v94, v241, s[30:31]
	v_cmp_gt_i32_e64 s[30:31], 59, v242
	v_cndmask_b32_e64 v110, v110, v241, s[34:35]
	v_cndmask_b32_e64 v95, v95, v241, s[28:29]
	v_cndmask_b32_e64 v111, v111, v241, s[30:31]
	v_max3_f32 v246, v80, v81, v82
	v_max3_f32 v247, v83, v84, v85
	v_max3_f32 v246, v246, v86, v87
	v_max3_f32 v247, v247, v88, v89
	v_max3_f32 v246, v246, v90, v91
	v_max3_f32 v247, v247, v92, v93
	v_max3_f32 v246, v246, v94, v95
	v_max3_f32 v247, v247, v96, v97
	v_max3_f32 v246, v246, v98, v99
	v_max3_f32 v247, v247, v100, v101
	v_max3_f32 v246, v246, v102, v103
	v_max3_f32 v247, v247, v104, v105
	v_max3_f32 v246, v246, v106, v107
	v_max3_f32 v247, v247, v108, v109
	v_max3_f32 v246, v246, v110, v111
	v_max_f32_e32 v248, v246, v247
	v_mov_b32_e32 v246, v248
	s_nop 1
	v_permlane32_swap_b32_e32 v248, v246
	v_max_f32_e32 v248, v248, v246
	s_mov_b32 s26, 0
	v_cmp_lt_f32_e32 vcc, s87, v248
	s_cmp_lg_u64 vcc, 0
	s_cbranch_scc1 .Lat_rare_T2
.Lat_cont_T2:
	v_add_u32_e32 v244, s18, v219
	v_mfma_f32_32x32x16_bf16 v[0:15], v[160:163], v[214:217], v[0:15]
	v_exp_f32_e32 v80, v80
	v_exp_f32_e32 v81, v81
	s_waitcnt lgkmcnt(12)
	ds_read_b64_tr_b16 v[214:215], v243 offset:49152
	ds_read_b64_tr_b16 v[216:217], v243 offset:49664
	v_mfma_f32_32x32x16_bf16 v[16:31], v[160:163], v[112:115], v[16:31]
	v_exp_f32_e32 v82, v82
	v_exp_f32_e32 v83, v83
	s_waitcnt lgkmcnt(12)
	ds_read_b64_tr_b16 v[112:113], v243 offset:53248
	ds_read_b64_tr_b16 v[114:115], v243 offset:53760
	v_mfma_f32_32x32x16_bf16 v[0:15], v[164:167], v[116:119], v[0:15]
	v_exp_f32_e32 v84, v84
	v_exp_f32_e32 v85, v85
	s_waitcnt lgkmcnt(12)
	ds_read_b64_tr_b16 v[116:117], v243 offset:50176
	ds_read_b64_tr_b16 v[118:119], v243 offset:50688
	v_mfma_f32_32x32x16_bf16 v[16:31], v[164:167], v[120:123], v[16:31]
	v_exp_f32_e32 v86, v86
	v_exp_f32_e32 v87, v87
	s_waitcnt lgkmcnt(12)
	ds_read_b64_tr_b16 v[120:121], v243 offset:54272
	ds_read_b64_tr_b16 v[122:123], v243 offset:54784
	v_mfma_f32_32x32x16_bf16 v[0:15], v[168:171], v[124:127], v[0:15]
	v_exp_f32_e32 v88, v88
	v_exp_f32_e32 v89, v89
	s_waitcnt lgkmcnt(12)
	ds_read_b64_tr_b16 v[124:125], v243 offset:51200
	ds_read_b64_tr_b16 v[126:127], v243 offset:51712
	v_mfma_f32_32x32x16_bf16 v[16:31], v[168:171], v[128:131], v[16:31]
	v_exp_f32_e32 v90, v90
	v_exp_f32_e32 v91, v91
	s_waitcnt lgkmcnt(12)
	ds_read_b64_tr_b16 v[128:129], v243 offset:55296
	ds_read_b64_tr_b16 v[130:131], v243 offset:55808
	v_mfma_f32_32x32x16_bf16 v[0:15], v[172:175], v[132:135], v[0:15]
	v_exp_f32_e32 v92, v92
	v_exp_f32_e32 v93, v93
	s_waitcnt lgkmcnt(12)
	ds_read_b64_tr_b16 v[132:133], v243 offset:52224
	ds_read_b64_tr_b16 v[134:135], v243 offset:52736
	v_mfma_f32_32x32x16_bf16 v[16:31], v[172:175], v[136:139], v[16:31]
	v_exp_f32_e32 v94, v94
	v_exp_f32_e32 v95, v95
	s_waitcnt lgkmcnt(12)
	ds_read_b64_tr_b16 v[136:137], v243 offset:56320
	ds_read_b64_tr_b16 v[138:139], v243 offset:56832
	v_mfma_f32_32x32x16_bf16 v[32:47], v[160:163], v[214:217], v[32:47]
	v_exp_f32_e32 v96, v96
	v_exp_f32_e32 v97, v97
	s_waitcnt lgkmcnt(12)
	ds_read_b128 v[176:179], v244 offset:0
	ds_read_b128 v[180:183], v244 offset:512
	v_mfma_f32_32x32x16_bf16 v[48:63], v[160:163], v[112:115], v[48:63]
	v_exp_f32_e32 v98, v98
	v_exp_f32_e32 v99, v99
	s_waitcnt lgkmcnt(12)
	ds_read_b128 v[184:187], v244 offset:2048
	ds_read_b128 v[188:191], v244 offset:2560
	v_mfma_f32_32x32x16_bf16 v[32:47], v[164:167], v[116:119], v[32:47]
	v_exp_f32_e32 v100, v100
	v_exp_f32_e32 v101, v101
	s_waitcnt lgkmcnt(12)
	ds_read_b128 v[192:195], v244 offset:4096
	ds_read_b128 v[196:199], v244 offset:4608
	v_mfma_f32_32x32x16_bf16 v[48:63], v[164:167], v[120:123], v[48:63]
	v_exp_f32_e32 v102, v102
	v_exp_f32_e32 v103, v103
	s_waitcnt lgkmcnt(12)
	ds_read_b128 v[200:203], v244 offset:6144
	ds_read_b128 v[206:209], v244 offset:6656
	v_mfma_f32_32x32x16_bf16 v[32:47], v[168:171], v[124:127], v[32:47]
	v_exp_f32_e32 v104, v104
	v_exp_f32_e32 v105, v105
	s_waitcnt lgkmcnt(12)
	v_mfma_f32_32x32x16_bf16 v[48:63], v[168:171], v[128:131], v[48:63]
	v_exp_f32_e32 v106, v106
	v_exp_f32_e32 v107, v107
	s_waitcnt lgkmcnt(10)
	v_mfma_f32_32x32x16_bf16 v[32:47], v[172:175], v[132:135], v[32:47]
	v_exp_f32_e32 v108, v108
	v_exp_f32_e32 v109, v109
	s_waitcnt lgkmcnt(8)
	v_mfma_f32_32x32x16_bf16 v[48:63], v[172:175], v[136:139], v[48:63]
	v_exp_f32_e32 v110, v110
	v_exp_f32_e32 v111, v111
	s_waitcnt vmcnt(0) lgkmcnt(0)
	s_barrier
	s_cmp_eq_u32 s26, 0
	s_cbranch_scc1 .Lat_noresc_T2
	s_waitcnt lgkmcnt(0)
	ds_read_b128 v[214:217], v227 offset:0
	s_waitcnt lgkmcnt(0)
	v_pk_mul_f32 v[0:1], v[0:1], v[214:215]
	v_pk_mul_f32 v[2:3], v[2:3], v[216:217]
	v_pk_mul_f32 v[16:17], v[16:17], v[214:215]
	v_pk_mul_f32 v[18:19], v[18:19], v[216:217]
	v_pk_mul_f32 v[32:33], v[32:33], v[214:215]
	v_pk_mul_f32 v[34:35], v[34:35], v[216:217]
	v_pk_mul_f32 v[48:49], v[48:49], v[214:215]
	v_pk_mul_f32 v[50:51], v[50:51], v[216:217]
	ds_read_b128 v[214:217], v227 offset:32
	s_waitcnt lgkmcnt(0)
	v_pk_mul_f32 v[4:5], v[4:5], v[214:215]
	v_pk_mul_f32 v[6:7], v[6:7], v[216:217]
	v_pk_mul_f32 v[20:21], v[20:21], v[214:215]
	v_pk_mul_f32 v[22:23], v[22:23], v[216:217]
	v_pk_mul_f32 v[36:37], v[36:37], v[214:215]
	v_pk_mul_f32 v[38:39], v[38:39], v[216:217]
	v_pk_mul_f32 v[52:53], v[52:53], v[214:215]
	v_pk_mul_f32 v[54:55], v[54:55], v[216:217]
	ds_read_b128 v[214:217], v227 offset:64
	s_waitcnt lgkmcnt(0)
	v_pk_mul_f32 v[8:9], v[8:9], v[214:215]
	v_pk_mul_f32 v[10:11], v[10:11], v[216:217]
	v_pk_mul_f32 v[24:25], v[24:25], v[214:215]
	v_pk_mul_f32 v[26:27], v[26:27], v[216:217]
	v_pk_mul_f32 v[40:41], v[40:41], v[214:215]
	v_pk_mul_f32 v[42:43], v[42:43], v[216:217]
	v_pk_mul_f32 v[56:57], v[56:57], v[214:215]
	v_pk_mul_f32 v[58:59], v[58:59], v[216:217]
	ds_read_b128 v[214:217], v227 offset:96
	s_waitcnt lgkmcnt(0)
	v_pk_mul_f32 v[12:13], v[12:13], v[214:215]
	v_pk_mul_f32 v[14:15], v[14:15], v[216:217]
	v_pk_mul_f32 v[28:29], v[28:29], v[214:215]
	v_pk_mul_f32 v[30:31], v[30:31], v[216:217]
	v_pk_mul_f32 v[44:45], v[44:45], v[214:215]
	v_pk_mul_f32 v[46:47], v[46:47], v[216:217]
	v_pk_mul_f32 v[60:61], v[60:61], v[214:215]
	v_pk_mul_f32 v[62:63], v[62:63], v[216:217]

;   #define RESC() do{ if(resc){ asm volatile("s_waitcnt lgkmcnt(0)":::"memory"); \
;       _Pragma("unroll") for(int d_=0;d_<2;++d_) _Pragma("unroll") for(int r=0;r<16;++r)o[d_][r]*=wsf[crow(r,hi)]; } }while(0)
; __device__ __forceinline__ void cmask(f32x16&p0,f32x16&p1,int jb,int qrel,int hi){
;   const float NEG=-INFINITY; int kb=64*jb+4*hi;
;   #pragma unroll
;   for(int r=0;r<16;++r){int kv=kb+(r&3)+8*(r>>2); if(kv>qrel)p0[r]=NEG; if(kv+32>qrel)p1[r]=NEG;}
; }
; template<int THRL> __device__ __forceinline__ void attn_unit(int b,int qc,int vc,int qb,const bf16*Q,const bf16*__restrict__ K,const bf16*__restrict__ V,bf16*O,char*shm,const int tid){
;     ...
;   STEP(pB0,pB1,pA0,pA1,NT-1,false,false,false); RESC();
.Lat_step_T1:
	v_add_u32_e32 v243, s16, v204
	ds_read_b64_tr_b16 v[214:215], v243 offset:24576
	ds_read_b64_tr_b16 v[216:217], v243 offset:25088
	v_mfma_f32_32x32x16_bf16 v[112:127], v[176:179], v[144:147], v[64:79]
	v_add_f32_e32 v245, v80, v81
	v_add_f32_e32 v245, v82, v245
	v_add_f32_e32 v245, v83, v245
	v_add_f32_e32 v245, v84, v245
	v_add_f32_e32 v245, v85, v245
	v_cvt_pk_bf16_f32 v160, v80, v81
	v_cvt_pk_bf16_f32 v161, v82, v83
	ds_read_b64_tr_b16 v[80:81], v243 offset:28672
	ds_read_b64_tr_b16 v[82:83], v243 offset:29184
	v_mfma_f32_32x32x16_bf16 v[128:143], v[180:183], v[144:147], v[64:79]
	v_add_f32_e32 v245, v86, v245
	v_add_f32_e32 v245, v87, v245
	v_add_f32_e32 v245, v88, v245
	v_add_f32_e32 v245, v89, v245
	v_cvt_pk_bf16_f32 v162, v84, v85
	v_cvt_pk_bf16_f32 v163, v86, v87
	ds_read_b64_tr_b16 v[84:85], v243 offset:25600
	ds_read_b64_tr_b16 v[86:87], v243 offset:26112
	v_mfma_f32_32x32x16_bf16 v[112:127], v[184:187], v[148:151], v[112:127]
	v_add_f32_e32 v245, v90, v245
	v_add_f32_e32 v245, v91, v245
	v_add_f32_e32 v245, v92, v245
	v_add_f32_e32 v245, v93, v245
	v_cvt_pk_bf16_f32 v164, v88, v89
	v_cvt_pk_bf16_f32 v165, v90, v91
	ds_read_b64_tr_b16 v[88:89], v243 offset:29696
	ds_read_b64_tr_b16 v[90:91], v243 offset:30208
	v_mfma_f32_32x32x16_bf16 v[128:143], v[188:191], v[148:151], v[128:143]
	v_add_f32_e32 v245, v94, v245
	v_add_f32_e32 v245, v95, v245
	v_add_f32_e32 v245, v96, v245
	v_add_f32_e32 v245, v97, v245
	v_cvt_pk_bf16_f32 v166, v92, v93
	v_cvt_pk_bf16_f32 v167, v94, v95
	ds_read_b64_tr_b16 v[92:93], v243 offset:26624
	ds_read_b64_tr_b16 v[94:95], v243 offset:27136
	v_mfma_f32_32x32x16_bf16 v[112:127], v[192:195], v[152:155], v[112:127]
	v_add_f32_e32 v245, v98, v245
	v_add_f32_e32 v245, v99, v245
	v_add_f32_e32 v245, v100, v245
	v_add_f32_e32 v245, v101, v245
	v_cvt_pk_bf16_f32 v168, v96, v97
	v_cvt_pk_bf16_f32 v169, v98, v99
	ds_read_b64_tr_b16 v[96:97], v243 offset:30720
	ds_read_b64_tr_b16 v[98:99], v243 offset:31232
	v_mfma_f32_32x32x16_bf16 v[128:143], v[196:199], v[152:155], v[128:143]
	v_add_f32_e32 v245, v102, v245
	v_add_f32_e32 v245, v103, v245
	v_add_f32_e32 v245, v104, v245
	v_add_f32_e32 v245, v105, v245
	v_cvt_pk_bf16_f32 v170, v100, v101
	v_cvt_pk_bf16_f32 v171, v102, v103
	ds_read_b64_tr_b16 v[100:101], v243 offset:27648
	ds_read_b64_tr_b16 v[102:103], v243 offset:28160
	v_mfma_f32_32x32x16_bf16 v[112:127], v[200:203], v[156:159], v[112:127]
	v_add_f32_e32 v245, v106, v245
	v_add_f32_e32 v245, v107, v245
	v_add_f32_e32 v245, v108, v245
	v_add_f32_e32 v245, v109, v245
	v_cvt_pk_bf16_f32 v172, v104, v105
	v_cvt_pk_bf16_f32 v173, v106, v107
	s_waitcnt lgkmcnt(12)
	ds_read_b64_tr_b16 v[104:105], v243 offset:31744
	ds_read_b64_tr_b16 v[106:107], v243 offset:32256
	v_mfma_f32_32x32x16_bf16 v[128:143], v[206:209], v[156:159], v[128:143]
	v_add_f32_e32 v245, v110, v245
	v_add_f32_e32 v245, v111, v245
	v_cvt_pk_bf16_f32 v174, v108, v109
	v_cvt_pk_bf16_f32 v175, v110, v111
	v_add_f32_e32 v211, v211, v245
	s_nop 6
	v_add_u32_e32 v242, 0xffffff40, v225
	v_cmp_gt_i32_e64 s[28:29], 0, v242
	v_cmp_gt_i32_e64 s[30:31], 32, v242
	v_cmp_gt_i32_e64 s[34:35], 1, v242
	v_cndmask_b32_e64 v112, v112, v241, s[28:29]
	v_cmp_gt_i32_e64 s[28:29], 33, v242
	v_cndmask_b32_e64 v128, v128, v241, s[30:31]
	v_cmp_gt_i32_e64 s[30:31], 2, v242
	v_cndmask_b32_e64 v113, v113, v241, s[34:35]
	v_cmp_gt_i32_e64 s[34:35], 34, v242
	v_cndmask_b32_e64 v129, v129, v241, s[28:29]
	v_cmp_gt_i32_e64 s[28:29], 3, v242
	v_cndmask_b32_e64 v114, v114, v241, s[30:31]
	v_cmp_gt_i32_e64 s[30:31], 35, v242
	v_cndmask_b32_e64 v130, v130, v241, s[34:35]
	v_cmp_gt_i32_e64 s[34:35], 8, v242
	v_cndmask_b32_e64 v115, v115, v241, s[28:29]
	v_cmp_gt_i32_e64 s[28:29], 40, v242
	v_cndmask_b32_e64 v131, v131, v241, s[30:31]
	v_cmp_gt_i32_e64 s[30:31], 9, v242
	v_cndmask_b32_e64 v116, v116, v241, s[34:35]
	v_cmp_gt_i32_e64 s[34:35], 41, v242
	v_cndmask_b32_e64 v132, v132, v241, s[28:29]
	v_cmp_gt_i32_e64 s[28:29], 10, v242
	v_cndmask_b32_e64 v117, v117, v241, s[30:31]
	v_cmp_gt_i32_e64 s[30:31], 42, v242
	v_cndmask_b32_e64 v133, v133, v241, s[34:35]
	v_cmp_gt_i32_e64 s[34:35], 11, v242
	v_cndmask_b32_e64 v118, v118, v241, s[28:29]
	v_cmp_gt_i32_e64 s[28:29], 43, v242
	v_cndmask_b32_e64 v134, v134, v241, s[30:31]
	v_cmp_gt_i32_e64 s[30:31], 16, v242
	v_cndmask_b32_e64 v119, v119, v241, s[34:35]
	v_cmp_gt_i32_e64 s[34:35], 48, v242
	v_cndmask_b32_e64 v135, v135, v241, s[28:29]
	v_cmp_gt_i32_e64 s[28:29], 17, v242
	v_cndmask_b32_e64 v120, v120, v241, s[30:31]
	v_cmp_gt_i32_e64 s[30:31], 49, v242
	v_cndmask_b32_e64 v136, v136, v241, s[34:35]
	v_cmp_gt_i32_e64 s[34:35], 18, v242
	v_cndmask_b32_e64 v121, v121, v241, s[28:29]
	v_cmp_gt_i32_e64 s[28:29], 50, v242
	v_cndmask_b32_e64 v137, v137, v241, s[30:31]
	v_cmp_gt_i32_e64 s[30:31], 19, v242
	v_cndmask_b32_e64 v122, v122, v241, s[34:35]
	v_cmp_gt_i32_e64 s[34:35], 51, v242
	v_cndmask_b32_e64 v138, v138, v241, s[28:29]
	v_cmp_gt_i32_e64 s[28:29], 24, v242
	v_cndmask_b32_e64 v123, v123, v241, s[30:31]
	v_cmp_gt_i32_e64 s[30:31], 56, v242
	v_cndmask_b32_e64 v139, v139, v241, s[34:35]
	v_cmp_gt_i32_e64 s[34:35], 25, v242
	v_cndmask_b32_e64 v124, v124, v241, s[28:29]
	v_cmp_gt_i32_e64 s[28:29], 57, v242
	v_cndmask_b32_e64 v140, v140, v241, s[30:31]
	v_cmp_gt_i32_e64 s[30:31], 26, v242
	v_cndmask_b32_e64 v125, v125, v241, s[34:35]
	v_cmp_gt_i32_e64 s[34:35], 58, v242
	v_cndmask_b32_e64 v141, v141, v241, s[28:29]
	v_cmp_gt_i32_e64 s[28:29], 27, v242
	v_cndmask_b32_e64 v126, v126, v241, s[30:31]
	v_cmp_gt_i32_e64 s[30:31], 59, v242
	v_cndmask_b32_e64 v142, v142, v241, s[34:35]
	v_cndmask_b32_e64 v127, v127, v241, s[28:29]
	v_cndmask_b32_e64 v143, v143, v241, s[30:31]
	v_max3_f32 v246, v112, v113, v114
	v_max3_f32 v247, v115, v116, v117
	v_max3_f32 v246, v246, v118, v119
	v_max3_f32 v247, v247, v120, v121
	v_max3_f32 v246, v246, v122, v123
	v_max3_f32 v247, v247, v124, v125
	v_max3_f32 v246, v246, v126, v127
	v_max3_f32 v247, v247, v128, v129
	v_max3_f32 v246, v246, v130, v131
	v_max3_f32 v247, v247, v132, v133
	v_max3_f32 v246, v246, v134, v135
	v_max3_f32 v247, v247, v136, v137
	v_max3_f32 v246, v246, v138, v139
	v_max3_f32 v247, v247, v140, v141
	v_max3_f32 v246, v246, v142, v143
	v_max_f32_e32 v248, v246, v247
	v_mov_b32_e32 v246, v248
	s_nop 1
	v_permlane32_swap_b32_e32 v248, v246
	v_max_f32_e32 v248, v248, v246
	s_mov_b32 s26, 0
	v_cmp_lt_f32_e32 vcc, s87, v248
	s_cmp_lg_u64 vcc, 0
	s_cbranch_scc1 .Lat_rare_T1
.Lat_cont_T1:
	v_mfma_f32_32x32x16_bf16 v[0:15], v[160:163], v[214:217], v[0:15]
	v_exp_f32_e32 v112, v112
	v_exp_f32_e32 v113, v113
	s_waitcnt lgkmcnt(12)
	ds_read_b64_tr_b16 v[214:215], v243 offset:49152
	ds_read_b64_tr_b16 v[216:217], v243 offset:49664
	v_mfma_f32_32x32x16_bf16 v[16:31], v[160:163], v[80:83], v[16:31]
	v_exp_f32_e32 v114, v114
	v_exp_f32_e32 v115, v115
	s_waitcnt lgkmcnt(12)
	ds_read_b64_tr_b16 v[80:81], v243 offset:53248
	ds_read_b64_tr_b16 v[82:83], v243 offset:53760
	v_mfma_f32_32x32x16_bf16 v[0:15], v[164:167], v[84:87], v[0:15]
	v_exp_f32_e32 v116, v116
	v_exp_f32_e32 v117, v117
	s_waitcnt lgkmcnt(12)
	ds_read_b64_tr_b16 v[84:85], v243 offset:50176
	ds_read_b64_tr_b16 v[86:87], v243 offset:50688
	v_mfma_f32_32x32x16_bf16 v[16:31], v[164:167], v[88:91], v[16:31]
	v_exp_f32_e32 v118, v118
	v_exp_f32_e32 v119, v119
	s_waitcnt lgkmcnt(12)
	ds_read_b64_tr_b16 v[88:89], v243 offset:54272
	ds_read_b64_tr_b16 v[90:91], v243 offset:54784
	v_mfma_f32_32x32x16_bf16 v[0:15], v[168:171], v[92:95], v[0:15]
	v_exp_f32_e32 v120, v120
	v_exp_f32_e32 v121, v121
	s_waitcnt lgkmcnt(12)
	ds_read_b64_tr_b16 v[92:93], v243 offset:51200
	ds_read_b64_tr_b16 v[94:95], v243 offset:51712
	v_mfma_f32_32x32x16_bf16 v[16:31], v[168:171], v[96:99], v[16:31]
	v_exp_f32_e32 v122, v122
	v_exp_f32_e32 v123, v123
	s_waitcnt lgkmcnt(12)
	ds_read_b64_tr_b16 v[96:97], v243 offset:55296
	ds_read_b64_tr_b16 v[98:99], v243 offset:55808
	v_mfma_f32_32x32x16_bf16 v[0:15], v[172:175], v[100:103], v[0:15]
	v_exp_f32_e32 v124, v124
	v_exp_f32_e32 v125, v125
	s_waitcnt lgkmcnt(12)
	ds_read_b64_tr_b16 v[100:101], v243 offset:52224
	ds_read_b64_tr_b16 v[102:103], v243 offset:52736
	v_mfma_f32_32x32x16_bf16 v[16:31], v[172:175], v[104:107], v[16:31]
	v_exp_f32_e32 v126, v126
	v_exp_f32_e32 v127, v127
	s_waitcnt lgkmcnt(12)
	ds_read_b64_tr_b16 v[104:105], v243 offset:56320
	ds_read_b64_tr_b16 v[106:107], v243 offset:56832
	v_mfma_f32_32x32x16_bf16 v[32:47], v[160:163], v[214:217], v[32:47]
	v_exp_f32_e32 v128, v128
	v_exp_f32_e32 v129, v129
	s_waitcnt lgkmcnt(12)
	v_mfma_f32_32x32x16_bf16 v[48:63], v[160:163], v[80:83], v[48:63]
	v_exp_f32_e32 v130, v130
	v_exp_f32_e32 v131, v131
	s_waitcnt lgkmcnt(10)
	v_mfma_f32_32x32x16_bf16 v[32:47], v[164:167], v[84:87], v[32:47]
	v_exp_f32_e32 v132, v132
	v_exp_f32_e32 v133, v133
	s_waitcnt lgkmcnt(8)
	v_mfma_f32_32x32x16_bf16 v[48:63], v[164:167], v[88:91], v[48:63]
	v_exp_f32_e32 v134, v134
	v_exp_f32_e32 v135, v135
	s_waitcnt lgkmcnt(6)
	v_mfma_f32_32x32x16_bf16 v[32:47], v[168:171], v[92:95], v[32:47]
	v_exp_f32_e32 v136, v136
	v_exp_f32_e32 v137, v137
	s_waitcnt lgkmcnt(4)
	v_mfma_f32_32x32x16_bf16 v[48:63], v[168:171], v[96:99], v[48:63]
	v_exp_f32_e32 v138, v138
	v_exp_f32_e32 v139, v139
	s_waitcnt lgkmcnt(2)
	v_mfma_f32_32x32x16_bf16 v[32:47], v[172:175], v[100:103], v[32:47]
	v_exp_f32_e32 v140, v140
	v_exp_f32_e32 v141, v141
	s_waitcnt lgkmcnt(0)
	v_mfma_f32_32x32x16_bf16 v[48:63], v[172:175], v[104:107], v[48:63]
	v_exp_f32_e32 v142, v142
	v_exp_f32_e32 v143, v143
	s_cmp_eq_u32 s26, 0
	s_cbranch_scc1 .Lat_noresc_T1
	s_waitcnt lgkmcnt(0)
	ds_read_b128 v[214:217], v227 offset:0
	s_waitcnt lgkmcnt(0)
	v_pk_mul_f32 v[0:1], v[0:1], v[214:215]
	v_pk_mul_f32 v[2:3], v[2:3], v[216:217]
	v_pk_mul_f32 v[16:17], v[16:17], v[214:215]
	v_pk_mul_f32 v[18:19], v[18:19], v[216:217]
	v_pk_mul_f32 v[32:33], v[32:33], v[214:215]
	v_pk_mul_f32 v[34:35], v[34:35], v[216:217]
	v_pk_mul_f32 v[48:49], v[48:49], v[214:215]
	v_pk_mul_f32 v[50:51], v[50:51], v[216:217]
	ds_read_b128 v[214:217], v227 offset:32
	s_waitcnt lgkmcnt(0)
	v_pk_mul_f32 v[4:5], v[4:5], v[214:215]
	v_pk_mul_f32 v[6:7], v[6:7], v[216:217]
	v_pk_mul_f32 v[20:21], v[20:21], v[214:215]
	v_pk_mul_f32 v[22:23], v[22:23], v[216:217]
	v_pk_mul_f32 v[36:37], v[36:37], v[214:215]
	v_pk_mul_f32 v[38:39], v[38:39], v[216:217]
	v_pk_mul_f32 v[52:53], v[52:53], v[214:215]
	v_pk_mul_f32 v[54:55], v[54:55], v[216:217]
	ds_read_b128 v[214:217], v227 offset:64
	s_waitcnt lgkmcnt(0)
	v_pk_mul_f32 v[8:9], v[8:9], v[214:215]
	v_pk_mul_f32 v[10:11], v[10:11], v[216:217]
	v_pk_mul_f32 v[24:25], v[24:25], v[214:215]
	v_pk_mul_f32 v[26:27], v[26:27], v[216:217]
	v_pk_mul_f32 v[40:41], v[40:41], v[214:215]
	v_pk_mul_f32 v[42:43], v[42:43], v[216:217]
	v_pk_mul_f32 v[56:57], v[56:57], v[214:215]
	v_pk_mul_f32 v[58:59], v[58:59], v[216:217]
	ds_read_b128 v[214:217], v227 offset:96
	s_waitcnt lgkmcnt(0)
	v_pk_mul_f32 v[12:13], v[12:13], v[214:215]
	v_pk_mul_f32 v[14:15], v[14:15], v[216:217]
	v_pk_mul_f32 v[28:29], v[28:29], v[214:215]
	v_pk_mul_f32 v[30:31], v[30:31], v[216:217]
	v_pk_mul_f32 v[44:45], v[44:45], v[214:215]
	v_pk_mul_f32 v[46:47], v[46:47], v[216:217]
	v_pk_mul_f32 v[60:61], v[60:61], v[214:215]
	v_pk_mul_f32 v[62:63], v[62:63], v[216:217]
; __device__ __forceinline__ int crow(int r,int hi){return (r&3)+8*(r>>2)+4*hi;}
; #define SBAR() __builtin_amdgcn_sched_barrier(0)
;   #define PKW(P,B) cvtpk_s(P[B],P[B+1])
; __device__ __forceinline__ void pv(f32x16*o,int vb,bf16x8 pa0,bf16x8 pa1,bf16x8 pa2,bf16x8 pa3){
;   #pragma unroll
;   for(int d0=0;d0<2;++d0){s16x4 lo[4],hi[4];
;     #pragma unroll
;     for(int ks=0;ks<4;++ks){
;       asm volatile("ds_read_b64_tr_b16 %0,%1 offset:%c2":"=&v"(lo[ks]):"v"(vb),"i"(d0*4096+ks*1024):"memory");
;       asm volatile("ds_read_b64_tr_b16 %0,%1 offset:%c2":"=&v"(hi[ks]):"v"(vb),"i"(d0*4096+ks*1024+512):"memory");}
;     asm volatile("s_waitcnt lgkmcnt(0)":::"memory");SBAR();
;     ...
;     o[d0]=__builtin_amdgcn_mfma_f32_32x32x16_bf16(pa0,PK(0),o[d0],0,0,0);
;     o[d0]=__builtin_amdgcn_mfma_f32_32x32x16_bf16(pa1,PK(1),o[d0],0,0,0);
;     o[d0]=__builtin_amdgcn_mfma_f32_32x32x16_bf16(pa2,PK(2),o[d0],0,0,0);
;     o[d0]=__builtin_amdgcn_mfma_f32_32x32x16_bf16(pa3,PK(3),o[d0],0,0,0);
;     ...
;   }
; }
; template<int THRL> __device__ __forceinline__ void attn_unit(int b,int qc,int vc,int qb,const bf16*Q,const bf16*__restrict__ K,const bf16*__restrict__ V,bf16*O,char*shm,const int tid){
;     ...
;   { float sacc=pB0[0]+pB0[1]; _Pragma("unroll") for(int r=2;r<16;++r)sacc+=pB0[r]; _Pragma("unroll") for(int r=0;r<16;++r)sacc+=pB1[r]; l_reg+=sacc;
;     pw0=(u32x4){PKW(pB0,0),PKW(pB0,2),PKW(pB0,4),PKW(pB0,6)};pw1=(u32x4){PKW(pB0,8),PKW(pB0,10),PKW(pB0,12),PKW(pB0,14)};pw2=(u32x4){PKW(pB1,0),PKW(pB1,2),PKW(pB1,4),PKW(pB1,6)};pw3=(u32x4){PKW(pB1,8),PKW(pB1,10),PKW(pB1,12),PKW(pB1,14)};
;     SBAR(); pv(o,vb0+sl_cur,PAF(0),PAF(1),PAF(2),PAF(3)); }
;     ...
;   {auto rr=__builtin_amdgcn_permlane32_swap(__float_as_uint(l_reg),__float_as_uint(l_reg),false,false);l_reg=__uint_as_float(rr[0])+__uint_as_float(rr[1]);}
;   if(hi==0)wsf[32+r32]=l_reg;asm volatile("s_waitcnt lgkmcnt(0)":::"memory");
;   float rli[16];
;   #pragma unroll
;   for(int r=0;r<16;++r)rli[r]=__builtin_amdgcn_rcpf(wsf[32+crow(r,hi)]);
.Lat_noresc_T1:
	v_add_u32_e32 v243, s17, v204
	v_add_f32_e32 v245, v112, v113
	v_add_f32_e32 v245, v114, v245
	v_add_f32_e32 v245, v115, v245
	v_add_f32_e32 v245, v116, v245
	v_add_f32_e32 v245, v117, v245
	v_cvt_pk_bf16_f32 v160, v112, v113
	v_cvt_pk_bf16_f32 v161, v114, v115
	v_add_f32_e32 v245, v118, v245
	v_add_f32_e32 v245, v119, v245
	v_add_f32_e32 v245, v120, v245
	v_add_f32_e32 v245, v121, v245
	v_cvt_pk_bf16_f32 v162, v116, v117
	v_cvt_pk_bf16_f32 v163, v118, v119
	v_add_f32_e32 v245, v122, v245
	v_add_f32_e32 v245, v123, v245
	v_add_f32_e32 v245, v124, v245
	v_add_f32_e32 v245, v125, v245
	v_cvt_pk_bf16_f32 v164, v120, v121
	v_cvt_pk_bf16_f32 v165, v122, v123
	v_add_f32_e32 v245, v126, v245
	v_add_f32_e32 v245, v127, v245
	v_add_f32_e32 v245, v128, v245
	v_add_f32_e32 v245, v129, v245
	v_cvt_pk_bf16_f32 v166, v124, v125
	v_cvt_pk_bf16_f32 v167, v126, v127
	v_add_f32_e32 v245, v130, v245
	v_add_f32_e32 v245, v131, v245
	v_add_f32_e32 v245, v132, v245
	v_add_f32_e32 v245, v133, v245
	v_cvt_pk_bf16_f32 v168, v128, v129
	v_cvt_pk_bf16_f32 v169, v130, v131
	v_add_f32_e32 v245, v134, v245
	v_add_f32_e32 v245, v135, v245
	v_add_f32_e32 v245, v136, v245
	v_add_f32_e32 v245, v137, v245
	v_cvt_pk_bf16_f32 v170, v132, v133
	v_cvt_pk_bf16_f32 v171, v134, v135
	v_add_f32_e32 v245, v138, v245
	v_add_f32_e32 v245, v139, v245
	v_add_f32_e32 v245, v140, v245
	v_add_f32_e32 v245, v141, v245
	v_cvt_pk_bf16_f32 v172, v136, v137
	v_cvt_pk_bf16_f32 v173, v138, v139
	v_add_f32_e32 v245, v142, v245
	v_add_f32_e32 v245, v143, v245
	v_cvt_pk_bf16_f32 v174, v140, v141
	v_cvt_pk_bf16_f32 v175, v142, v143
	v_add_f32_e32 v211, v211, v245
	ds_read_b64_tr_b16 v[112:113], v243 offset:24576
	ds_read_b64_tr_b16 v[114:115], v243 offset:25088
	ds_read_b64_tr_b16 v[116:117], v243 offset:28672
	ds_read_b64_tr_b16 v[118:119], v243 offset:29184
	ds_read_b64_tr_b16 v[120:121], v243 offset:25600
	ds_read_b64_tr_b16 v[122:123], v243 offset:26112
	ds_read_b64_tr_b16 v[124:125], v243 offset:29696
	ds_read_b64_tr_b16 v[126:127], v243 offset:30208
	ds_read_b64_tr_b16 v[128:129], v243 offset:26624
	ds_read_b64_tr_b16 v[130:131], v243 offset:27136
	ds_read_b64_tr_b16 v[132:133], v243 offset:30720
	ds_read_b64_tr_b16 v[134:135], v243 offset:31232
	ds_read_b64_tr_b16 v[136:137], v243 offset:27648
	ds_read_b64_tr_b16 v[138:139], v243 offset:28160
	s_waitcnt lgkmcnt(12)
	ds_read_b64_tr_b16 v[140:141], v243 offset:31744
	ds_read_b64_tr_b16 v[142:143], v243 offset:32256
	v_mfma_f32_32x32x16_bf16 v[0:15], v[160:163], v[112:115], v[0:15]
	s_waitcnt lgkmcnt(12)
	v_mfma_f32_32x32x16_bf16 v[16:31], v[160:163], v[116:119], v[16:31]
	s_waitcnt lgkmcnt(10)
	v_mfma_f32_32x32x16_bf16 v[0:15], v[164:167], v[120:123], v[0:15]
	s_waitcnt lgkmcnt(8)
	v_mfma_f32_32x32x16_bf16 v[16:31], v[164:167], v[124:127], v[16:31]
	s_waitcnt lgkmcnt(6)
	v_mfma_f32_32x32x16_bf16 v[0:15], v[168:171], v[128:131], v[0:15]
	s_waitcnt lgkmcnt(4)
	v_mfma_f32_32x32x16_bf16 v[16:31], v[168:171], v[132:135], v[16:31]
	s_waitcnt lgkmcnt(2)
	v_mfma_f32_32x32x16_bf16 v[0:15], v[172:175], v[136:139], v[0:15]
	s_waitcnt lgkmcnt(0)
	v_mfma_f32_32x32x16_bf16 v[16:31], v[172:175], v[140:143], v[16:31]
	ds_read_b64_tr_b16 v[112:113], v243 offset:49152
	ds_read_b64_tr_b16 v[114:115], v243 offset:49664
	ds_read_b64_tr_b16 v[116:117], v243 offset:53248
	ds_read_b64_tr_b16 v[118:119], v243 offset:53760
	ds_read_b64_tr_b16 v[120:121], v243 offset:50176
	ds_read_b64_tr_b16 v[122:123], v243 offset:50688
	ds_read_b64_tr_b16 v[124:125], v243 offset:54272
	ds_read_b64_tr_b16 v[126:127], v243 offset:54784
	ds_read_b64_tr_b16 v[128:129], v243 offset:51200
	ds_read_b64_tr_b16 v[130:131], v243 offset:51712
	ds_read_b64_tr_b16 v[132:133], v243 offset:55296
	ds_read_b64_tr_b16 v[134:135], v243 offset:55808
	ds_read_b64_tr_b16 v[136:137], v243 offset:52224
	ds_read_b64_tr_b16 v[138:139], v243 offset:52736
	s_waitcnt lgkmcnt(12)
	ds_read_b64_tr_b16 v[140:141], v243 offset:56320
	ds_read_b64_tr_b16 v[142:143], v243 offset:56832
	v_mfma_f32_32x32x16_bf16 v[32:47], v[160:163], v[112:115], v[32:47]
	s_waitcnt lgkmcnt(12)
	v_mfma_f32_32x32x16_bf16 v[48:63], v[160:163], v[116:119], v[48:63]
	s_waitcnt lgkmcnt(10)
	v_mfma_f32_32x32x16_bf16 v[32:47], v[164:167], v[120:123], v[32:47]
	s_waitcnt lgkmcnt(8)
	v_mfma_f32_32x32x16_bf16 v[48:63], v[164:167], v[124:127], v[48:63]
	s_waitcnt lgkmcnt(6)
	v_mfma_f32_32x32x16_bf16 v[32:47], v[168:171], v[128:131], v[32:47]
	s_waitcnt lgkmcnt(4)
	v_mfma_f32_32x32x16_bf16 v[48:63], v[168:171], v[132:135], v[48:63]
	s_waitcnt lgkmcnt(2)
	v_mfma_f32_32x32x16_bf16 v[32:47], v[172:175], v[136:139], v[32:47]
	s_waitcnt lgkmcnt(0)
	v_mfma_f32_32x32x16_bf16 v[48:63], v[172:175], v[140:143], v[48:63]
	v_mov_b32_e32 v243, v211
	s_nop 1
	v_permlane32_swap_b32_e32 v211, v243
	v_add_f32_e32 v211, v211, v243
	ds_write_b32 v226, v211 offset:128
	s_waitcnt lgkmcnt(0)
	ds_read_b128 v[80:83], v227 offset:128
	ds_read_b128 v[84:87], v227 offset:160
	ds_read_b128 v[88:91], v227 offset:192
	ds_read_b128 v[92:95], v227 offset:224
	s_waitcnt lgkmcnt(0)
; __device__ __forceinline__ int crow(int r,int hi){return (r&3)+8*(r>>2)+4*hi;}
; template<int THRL> __device__ __forceinline__ void attn_unit(int b,int qc,int vc,int qb,const bf16*Q,const bf16*__restrict__ K,const bf16*__restrict__ V,bf16*O,char*shm,const int tid){
;     ...
;   float rli[16];
;   #pragma unroll
;   for(int r=0;r<16;++r)rli[r]=__builtin_amdgcn_rcpf(wsf[32+crow(r,hi)]);
;   bf16*Ow=O+(rowbase+q0+wid*QBLK)*DM+vc;
;   { bf16*stg=(bf16*)(shm+LDS_OST)+wid*2048;
;     #pragma unroll
;     for(int r=0;r<16;++r){const int orow=crow(r,hi);
;       #pragma unroll
;       for(int d0=0;d0<2;++d0)stg[orow*64+d0*32+r32]=__float2bfloat16(o[d0][r]*rli[r]);}
;     asm volatile("s_waitcnt lgkmcnt(0)":::"memory");
;     #pragma unroll
;     for(int i=0;i<4;++i){const int row=i*8+(lane>>3),ch=lane&7; const u32x4 v=*(const u32x4*)(stg+row*64+ch*8); ATTN_STORE16(Ow+(long)row*DM+ch*8,v);} }
	v_rcp_f32_e32 v80, v80
	v_rcp_f32_e32 v81, v81
	v_rcp_f32_e32 v82, v82
	v_rcp_f32_e32 v83, v83
	v_rcp_f32_e32 v84, v84
	v_rcp_f32_e32 v85, v85
	v_rcp_f32_e32 v86, v86
	v_rcp_f32_e32 v87, v87
	v_rcp_f32_e32 v88, v88
	v_rcp_f32_e32 v89, v89
	v_rcp_f32_e32 v90, v90
	v_rcp_f32_e32 v91, v91
	v_rcp_f32_e32 v92, v92
	v_rcp_f32_e32 v93, v93
	v_rcp_f32_e32 v94, v94
	v_rcp_f32_e32 v95, v95
	s_nop 0
	v_mul_f32_e32 v96, v0, v80
	v_cvt_pk_bf16_f32 v96, v96, v96
	ds_write_b16 v228, v96 offset:0
	v_mul_f32_e32 v97, v1, v81
	v_cvt_pk_bf16_f32 v97, v97, v97
	ds_write_b16 v228, v97 offset:128
	v_mul_f32_e32 v98, v2, v82
	v_cvt_pk_bf16_f32 v98, v98, v98
	ds_write_b16 v228, v98 offset:256
	v_mul_f32_e32 v99, v3, v83
	v_cvt_pk_bf16_f32 v99, v99, v99
	ds_write_b16 v228, v99 offset:384
	v_mul_f32_e32 v100, v4, v84
	v_cvt_pk_bf16_f32 v100, v100, v100
	ds_write_b16 v228, v100 offset:1024
	v_mul_f32_e32 v101, v5, v85
	v_cvt_pk_bf16_f32 v101, v101, v101
	ds_write_b16 v228, v101 offset:1152
	v_mul_f32_e32 v102, v6, v86
	v_cvt_pk_bf16_f32 v102, v102, v102
	ds_write_b16 v228, v102 offset:1280
	v_mul_f32_e32 v103, v7, v87
	v_cvt_pk_bf16_f32 v103, v103, v103
	ds_write_b16 v228, v103 offset:1408
	v_mul_f32_e32 v104, v8, v88
	v_cvt_pk_bf16_f32 v104, v104, v104
	ds_write_b16 v228, v104 offset:2048
	v_mul_f32_e32 v105, v9, v89
	v_cvt_pk_bf16_f32 v105, v105, v105
	ds_write_b16 v228, v105 offset:2176
	v_mul_f32_e32 v106, v10, v90
	v_cvt_pk_bf16_f32 v106, v106, v106
	ds_write_b16 v228, v106 offset:2304
	v_mul_f32_e32 v107, v11, v91
	v_cvt_pk_bf16_f32 v107, v107, v107
	ds_write_b16 v228, v107 offset:2432
	v_mul_f32_e32 v108, v12, v92
	v_cvt_pk_bf16_f32 v108, v108, v108
	ds_write_b16 v228, v108 offset:3072
	v_mul_f32_e32 v109, v13, v93
	v_cvt_pk_bf16_f32 v109, v109, v109
	ds_write_b16 v228, v109 offset:3200
	v_mul_f32_e32 v110, v14, v94
	v_cvt_pk_bf16_f32 v110, v110, v110
	ds_write_b16 v228, v110 offset:3328
	v_mul_f32_e32 v111, v15, v95
	v_cvt_pk_bf16_f32 v111, v111, v111
	ds_write_b16 v228, v111 offset:3456
	v_mul_f32_e32 v96, v16, v80
	v_cvt_pk_bf16_f32 v96, v96, v96
	ds_write_b16 v228, v96 offset:64
	v_mul_f32_e32 v97, v17, v81
	v_cvt_pk_bf16_f32 v97, v97, v97
	ds_write_b16 v228, v97 offset:192
	v_mul_f32_e32 v98, v18, v82
	v_cvt_pk_bf16_f32 v98, v98, v98
	ds_write_b16 v228, v98 offset:320
	v_mul_f32_e32 v99, v19, v83
	v_cvt_pk_bf16_f32 v99, v99, v99
	ds_write_b16 v228, v99 offset:448
	v_mul_f32_e32 v100, v20, v84
	v_cvt_pk_bf16_f32 v100, v100, v100
	ds_write_b16 v228, v100 offset:1088
	v_mul_f32_e32 v101, v21, v85
	v_cvt_pk_bf16_f32 v101, v101, v101
	ds_write_b16 v228, v101 offset:1216
	v_mul_f32_e32 v102, v22, v86
	v_cvt_pk_bf16_f32 v102, v102, v102
	ds_write_b16 v228, v102 offset:1344
	v_mul_f32_e32 v103, v23, v87
	v_cvt_pk_bf16_f32 v103, v103, v103
	ds_write_b16 v228, v103 offset:1472
	v_mul_f32_e32 v104, v24, v88
	v_cvt_pk_bf16_f32 v104, v104, v104
	ds_write_b16 v228, v104 offset:2112
	v_mul_f32_e32 v105, v25, v89
	v_cvt_pk_bf16_f32 v105, v105, v105
	ds_write_b16 v228, v105 offset:2240
	v_mul_f32_e32 v106, v26, v90
	v_cvt_pk_bf16_f32 v106, v106, v106
	ds_write_b16 v228, v106 offset:2368
	v_mul_f32_e32 v107, v27, v91
	v_cvt_pk_bf16_f32 v107, v107, v107
	ds_write_b16 v228, v107 offset:2496
	v_mul_f32_e32 v108, v28, v92
	v_cvt_pk_bf16_f32 v108, v108, v108
	ds_write_b16 v228, v108 offset:3136
	v_mul_f32_e32 v109, v29, v93
	v_cvt_pk_bf16_f32 v109, v109, v109
	ds_write_b16 v228, v109 offset:3264
	v_mul_f32_e32 v110, v30, v94
	v_cvt_pk_bf16_f32 v110, v110, v110
	ds_write_b16 v228, v110 offset:3392
	v_mul_f32_e32 v111, v31, v95
	v_cvt_pk_bf16_f32 v111, v111, v111
	ds_write_b16 v228, v111 offset:3520
	s_waitcnt lgkmcnt(0)
	ds_read_b128 v[112:115], v229 offset:0
	ds_read_b128 v[116:119], v229 offset:1024
	ds_read_b128 v[120:123], v229 offset:2048
	ds_read_b128 v[124:127], v229 offset:3072
	s_waitcnt lgkmcnt(3)
	v_mov_b32_e32 v243, v251
	global_store_dwordx4 v243, v[112:115], s[6:7] offset:0
	s_nop 1
	s_waitcnt lgkmcnt(2)
	v_add_u32_e32 v243, 0x4000, v243
	global_store_dwordx4 v243, v[116:119], s[6:7] offset:0
	s_nop 1
	s_waitcnt lgkmcnt(1)
	v_add_u32_e32 v243, 0x4000, v243
	global_store_dwordx4 v243, v[120:123], s[6:7] offset:0
	s_nop 1
	s_waitcnt lgkmcnt(0)
	v_add_u32_e32 v243, 0x4000, v243
	global_store_dwordx4 v243, v[124:127], s[6:7] offset:0
	s_nop 1
	v_mul_f32_e32 v96, v32, v80
	v_cvt_pk_bf16_f32 v96, v96, v96
	ds_write_b16 v228, v96 offset:0
	v_mul_f32_e32 v97, v33, v81
	v_cvt_pk_bf16_f32 v97, v97, v97
	ds_write_b16 v228, v97 offset:128
	v_mul_f32_e32 v98, v34, v82
	v_cvt_pk_bf16_f32 v98, v98, v98
	ds_write_b16 v228, v98 offset:256
	v_mul_f32_e32 v99, v35, v83
	v_cvt_pk_bf16_f32 v99, v99, v99
	ds_write_b16 v228, v99 offset:384
	v_mul_f32_e32 v100, v36, v84
	v_cvt_pk_bf16_f32 v100, v100, v100
	ds_write_b16 v228, v100 offset:1024
	v_mul_f32_e32 v101, v37, v85
	v_cvt_pk_bf16_f32 v101, v101, v101
	ds_write_b16 v228, v101 offset:1152
	v_mul_f32_e32 v102, v38, v86
	v_cvt_pk_bf16_f32 v102, v102, v102
	ds_write_b16 v228, v102 offset:1280
	v_mul_f32_e32 v103, v39, v87
	v_cvt_pk_bf16_f32 v103, v103, v103
	ds_write_b16 v228, v103 offset:1408
	v_mul_f32_e32 v104, v40, v88
	v_cvt_pk_bf16_f32 v104, v104, v104
	ds_write_b16 v228, v104 offset:2048
	v_mul_f32_e32 v105, v41, v89
	v_cvt_pk_bf16_f32 v105, v105, v105
	ds_write_b16 v228, v105 offset:2176
	v_mul_f32_e32 v106, v42, v90
	v_cvt_pk_bf16_f32 v106, v106, v106
	ds_write_b16 v228, v106 offset:2304
	v_mul_f32_e32 v107, v43, v91
	v_cvt_pk_bf16_f32 v107, v107, v107
	ds_write_b16 v228, v107 offset:2432
	v_mul_f32_e32 v108, v44, v92
	v_cvt_pk_bf16_f32 v108, v108, v108
	ds_write_b16 v228, v108 offset:3072
	v_mul_f32_e32 v109, v45, v93
; __device__ __forceinline__ int crow(int r,int hi){return (r&3)+8*(r>>2)+4*hi;}
; template<int THRL> __device__ __forceinline__ void attn_unit(int b,int qc,int vc,int qb,const bf16*Q,const bf16*__restrict__ K,const bf16*__restrict__ V,bf16*O,char*shm,const int tid){
;     ...
;   { bf16*stg=(bf16*)(shm+LDS_OST)+wid*2048;
;     #pragma unroll
;     for(int r=0;r<16;++r){const int orow=crow(r,hi);
;       #pragma unroll
;       for(int d0=0;d0<2;++d0)stg[orow*64+d0*32+r32]=__float2bfloat16(o[d0][r]*rli[r]);}
;     asm volatile("s_waitcnt lgkmcnt(0)":::"memory");
;     #pragma unroll
;     for(int i=0;i<4;++i){const int row=i*8+(lane>>3),ch=lane&7; const u32x4 v=*(const u32x4*)(stg+row*64+ch*8); ATTN_STORE16(Ow+(long)row*DM+ch*8,v);} }
;   asm volatile("s_waitcnt lgkmcnt(0)\n\ts_barrier":::"memory");
	v_cvt_pk_bf16_f32 v109, v109, v109
	ds_write_b16 v228, v109 offset:3200
	v_mul_f32_e32 v110, v46, v94
	v_cvt_pk_bf16_f32 v110, v110, v110
	ds_write_b16 v228, v110 offset:3328
	v_mul_f32_e32 v111, v47, v95
	v_cvt_pk_bf16_f32 v111, v111, v111
	ds_write_b16 v228, v111 offset:3456
	v_mul_f32_e32 v96, v48, v80
	v_cvt_pk_bf16_f32 v96, v96, v96
	ds_write_b16 v228, v96 offset:64
	v_mul_f32_e32 v97, v49, v81
	v_cvt_pk_bf16_f32 v97, v97, v97
	ds_write_b16 v228, v97 offset:192
	v_mul_f32_e32 v98, v50, v82
	v_cvt_pk_bf16_f32 v98, v98, v98
	ds_write_b16 v228, v98 offset:320
	v_mul_f32_e32 v99, v51, v83
	v_cvt_pk_bf16_f32 v99, v99, v99
	ds_write_b16 v228, v99 offset:448
	v_mul_f32_e32 v100, v52, v84
	v_cvt_pk_bf16_f32 v100, v100, v100
	ds_write_b16 v228, v100 offset:1088
	v_mul_f32_e32 v101, v53, v85
	v_cvt_pk_bf16_f32 v101, v101, v101
	ds_write_b16 v228, v101 offset:1216
	v_mul_f32_e32 v102, v54, v86
	v_cvt_pk_bf16_f32 v102, v102, v102
	ds_write_b16 v228, v102 offset:1344
	v_mul_f32_e32 v103, v55, v87
	v_cvt_pk_bf16_f32 v103, v103, v103
	ds_write_b16 v228, v103 offset:1472
	v_mul_f32_e32 v104, v56, v88
	v_cvt_pk_bf16_f32 v104, v104, v104
	ds_write_b16 v228, v104 offset:2112
	v_mul_f32_e32 v105, v57, v89
	v_cvt_pk_bf16_f32 v105, v105, v105
	ds_write_b16 v228, v105 offset:2240
	v_mul_f32_e32 v106, v58, v90
	v_cvt_pk_bf16_f32 v106, v106, v106
	ds_write_b16 v228, v106 offset:2368
	v_mul_f32_e32 v107, v59, v91
	v_cvt_pk_bf16_f32 v107, v107, v107
	ds_write_b16 v228, v107 offset:2496
	v_mul_f32_e32 v108, v60, v92
	v_cvt_pk_bf16_f32 v108, v108, v108
	ds_write_b16 v228, v108 offset:3136
	v_mul_f32_e32 v109, v61, v93
	v_cvt_pk_bf16_f32 v109, v109, v109
	ds_write_b16 v228, v109 offset:3264
	v_mul_f32_e32 v110, v62, v94
	v_cvt_pk_bf16_f32 v110, v110, v110
	ds_write_b16 v228, v110 offset:3392
	v_mul_f32_e32 v111, v63, v95
	v_cvt_pk_bf16_f32 v111, v111, v111
	ds_write_b16 v228, v111 offset:3520
	s_waitcnt lgkmcnt(0)
	ds_read_b128 v[112:115], v229 offset:0
	ds_read_b128 v[116:119], v229 offset:1024
	ds_read_b128 v[120:123], v229 offset:2048
	ds_read_b128 v[124:127], v229 offset:3072
	s_waitcnt lgkmcnt(3)
	v_mov_b32_e32 v243, v251
	global_store_dwordx4 v243, v[112:115], s[6:7] offset:128
	s_nop 1
	s_waitcnt lgkmcnt(2)
	v_add_u32_e32 v243, 0x4000, v243
	global_store_dwordx4 v243, v[116:119], s[6:7] offset:128
	s_nop 1
	s_waitcnt lgkmcnt(1)
	v_add_u32_e32 v243, 0x4000, v243
	global_store_dwordx4 v243, v[120:123], s[6:7] offset:128
	s_nop 1
	s_waitcnt lgkmcnt(0)
	v_add_u32_e32 v243, 0x4000, v243
	global_store_dwordx4 v243, v[124:127], s[6:7] offset:128
	s_nop 1
	s_waitcnt lgkmcnt(0)
	s_barrier
	s_branch .Lat_unit_done
.Lat_rare_M1:
	v_max_f32_e32 v249, 0, v248
	v_exp_f32_e64 v250, -v249
	v_add_f32_e32 v210, v210, v249
	v_xor_b32_e32 v64, 0x80000000, v210
	v_mov_b32_e32 v65, v64
	v_mov_b32_e32 v66, v64
	v_mov_b32_e32 v67, v64
	v_mov_b32_e32 v68, v64
	v_mov_b32_e32 v69, v64
	v_mov_b32_e32 v70, v64
	v_mov_b32_e32 v71, v64
	v_mov_b32_e32 v72, v64
	v_mov_b32_e32 v73, v64
	v_mov_b32_e32 v74, v64
	v_mov_b32_e32 v75, v64
	v_mov_b32_e32 v76, v64
	v_mov_b32_e32 v77, v64
	v_mov_b32_e32 v78, v64
	v_mov_b32_e32 v79, v64
	ds_write_b32 v226, v250
	v_sub_f32_e32 v112, v112, v249
	v_sub_f32_e32 v113, v113, v249
	v_sub_f32_e32 v114, v114, v249
	v_sub_f32_e32 v115, v115, v249
	v_sub_f32_e32 v116, v116, v249
	v_sub_f32_e32 v117, v117, v249
	v_sub_f32_e32 v118, v118, v249
	v_sub_f32_e32 v119, v119, v249
	v_sub_f32_e32 v120, v120, v249
	v_sub_f32_e32 v121, v121, v249
	v_sub_f32_e32 v122, v122, v249
	v_sub_f32_e32 v123, v123, v249
	v_sub_f32_e32 v124, v124, v249
	v_sub_f32_e32 v125, v125, v249
	v_sub_f32_e32 v126, v126, v249
	v_sub_f32_e32 v127, v127, v249
	v_sub_f32_e32 v128, v128, v249
	v_sub_f32_e32 v129, v129, v249
	v_sub_f32_e32 v130, v130, v249
	v_sub_f32_e32 v131, v131, v249
	v_sub_f32_e32 v132, v132, v249
	v_sub_f32_e32 v133, v133, v249
	v_sub_f32_e32 v134, v134, v249
	v_sub_f32_e32 v135, v135, v249
	v_sub_f32_e32 v136, v136, v249
	v_sub_f32_e32 v137, v137, v249
	v_sub_f32_e32 v138, v138, v249
	v_sub_f32_e32 v139, v139, v249
	v_sub_f32_e32 v140, v140, v249
	v_sub_f32_e32 v141, v141, v249
	v_sub_f32_e32 v142, v142, v249
	v_sub_f32_e32 v143, v143, v249
	v_mul_f32_e32 v211, v211, v250
	s_mov_b32 s26, 1
	s_branch .Lat_cont_M1
.Lat_rare_M2:
	v_max_f32_e32 v249, 0, v248
	v_exp_f32_e64 v250, -v249
	v_add_f32_e32 v210, v210, v249
	v_xor_b32_e32 v64, 0x80000000, v210
	v_mov_b32_e32 v65, v64
	v_mov_b32_e32 v66, v64
	v_mov_b32_e32 v67, v64
	v_mov_b32_e32 v68, v64
	v_mov_b32_e32 v69, v64
	v_mov_b32_e32 v70, v64
	v_mov_b32_e32 v71, v64
	v_mov_b32_e32 v72, v64
	v_mov_b32_e32 v73, v64
	v_mov_b32_e32 v74, v64
	v_mov_b32_e32 v75, v64
	v_mov_b32_e32 v76, v64
	v_mov_b32_e32 v77, v64
	v_mov_b32_e32 v78, v64
	v_mov_b32_e32 v79, v64
	ds_write_b32 v226, v250
	v_sub_f32_e32 v80, v80, v249
	v_sub_f32_e32 v81, v81, v249
	v_sub_f32_e32 v82, v82, v249
	v_sub_f32_e32 v83, v83, v249
	v_sub_f32_e32 v84, v84, v249
	v_sub_f32_e32 v85, v85, v249
	v_sub_f32_e32 v86, v86, v249
	v_sub_f32_e32 v87, v87, v249
	v_sub_f32_e32 v88, v88, v249
	v_sub_f32_e32 v89, v89, v249
	v_sub_f32_e32 v90, v90, v249
	v_sub_f32_e32 v91, v91, v249
	v_sub_f32_e32 v92, v92, v249
	v_sub_f32_e32 v93, v93, v249
	v_sub_f32_e32 v94, v94, v249
	v_sub_f32_e32 v95, v95, v249
	v_sub_f32_e32 v96, v96, v249
	v_sub_f32_e32 v97, v97, v249
	v_sub_f32_e32 v98, v98, v249
	v_sub_f32_e32 v99, v99, v249
	v_sub_f32_e32 v100, v100, v249
	v_sub_f32_e32 v101, v101, v249
	v_sub_f32_e32 v102, v102, v249
	v_sub_f32_e32 v103, v103, v249
	v_sub_f32_e32 v104, v104, v249
	v_sub_f32_e32 v105, v105, v249
	v_sub_f32_e32 v106, v106, v249
	v_sub_f32_e32 v107, v107, v249
	v_sub_f32_e32 v108, v108, v249
	v_sub_f32_e32 v109, v109, v249
	v_sub_f32_e32 v110, v110, v249
	v_sub_f32_e32 v111, v111, v249
	v_mul_f32_e32 v211, v211, v250
	s_mov_b32 s26, 1
	s_branch .Lat_cont_M2

; __global__ void __launch_bounds__(NWAVES * 64, 2) fwd_kernel(Args args) {
;     ...
;                 for (int cm = 0; cm < 4; ++cm) { const int mp = cm >> 1, vh = cm & 1;
;                     for (int qi = 0; qi < 4; ++qi) {
;                         const int qb = (qi == 0) ? 15 - s4 : (qi == 1) ? 8 + s4 : (qi == 2) ? 7 - s4 : s4;
;                         int t2 = tidp; asm volatile("" : "+v"(t2));
;                         unsigned char* w2 = ws; asm volatile("" : "+s"(w2));
;                         attn_body::attn_unit<8>(b, (h * 2 + mp) * 64, h * 128 + vh * 64, qb, (const attn_body::bf16*)(w2 + WS_Q), (const attn_body::bf16*)(w2 + WS_K), (const attn_body::bf16*)(w2 + WS_V),
.Lat_unit_done:
	s_add_i32 s73, s73, 1
	s_cmp_lt_u32 s73, 4
	s_cbranch_scc1 .Lat_qi_loop
	s_add_i32 s72, s72, 1
	s_cmp_lt_u32 s72, 2
	s_cbranch_scc1 .Lat_mp_loop
